# GEMM epilogues: removed the denormal pre/post scaling around v_rsq_f32 at 13 sites (argument never below FLT_MIN; bit-identical)
# speedup vs baseline: 1.1177x; 1.0046x over previous
.LBB0_109:
	v_mov_b32_e32 v226, v224
	s_lshl_b32 s4, s76, 8
	s_add_i32 s4, s4, s20
	s_mov_b32 s35, 0x800000
	v_and_b32_e32 v183, 15, v226
	v_or_b32_e32 v150, s4, v183
	v_ashrrev_i32_e32 v151, 31, v150
	v_lshl_add_u64 v[136:137], v[150:151], 3, s[38:39]
	global_load_dwordx2 v[152:153], v[136:137], off
	global_load_dwordx2 v[134:135], v[136:137], off offset:128
	global_load_dwordx2 v[132:133], v[136:137], off offset:256
	s_nop 0
	global_load_dwordx2 v[136:137], v[136:137], off offset:384
	v_ashrrev_i32_e32 v0, 1, v226
	v_and_b32_e32 v0, -8, v0
	v_add_u32_e32 v130, s21, v0
	s_lshl_b32 s6, s76, 2
	s_add_i32 s6, s6, s11
	s_lshl_b32 s0, s78, 8
	s_ashr_i32 s1, s0, 31
	s_mul_i32 s7, s6, 0xb000
	s_mul_hi_i32 s5, s6, 0xb000
	s_add_u32 s7, s18, s7
	s_addc_u32 s5, s19, s5
	s_lshl_b64 s[80:81], s[0:1], 1
	s_add_u32 s76, s7, s80
	s_addc_u32 s77, s5, s81
	s_waitcnt vmcnt(0)
	v_ffbh_u32_e32 v0, v153
	v_min_u32_e32 v0, 32, v0
	v_lshlrev_b64 v[152:153], v0, v[152:153]
	v_min_u32_e32 v131, 1, v152
	v_or_b32_e32 v131, v153, v131
	v_cvt_f32_u32_e32 v131, v131
	v_sub_u32_e32 v0, 32, v0
	v_ldexp_f32 v0, v131, v0
	v_mul_f32_e32 v0, 0x33800000, v0
	v_fmamk_f32 v0, v0, 0x3a800000, v210
	s_nop 0
	v_rsq_f32_e32 v0, v0
	s_nop 0
	s_nop 0
	v_ashrrev_i32_e32 v131, 31, v130
	v_pk_mul_f32 v[172:173], v[128:129], v[0:1] op_sel_hi:[1,0]
	v_pk_mul_f32 v[170:171], v[126:127], v[0:1] op_sel_hi:[1,0]
	v_pk_mul_f32 v[156:157], v[124:125], v[0:1] op_sel_hi:[1,0]
	v_pk_mul_f32 v[158:159], v[122:123], v[0:1] op_sel_hi:[1,0]
	v_lshl_add_u64 v[122:123], v[130:131], 1, s[76:77]
	v_cmp_gt_u32_e32 vcc, 2, v183
	s_and_saveexec_b64 s[0:1], vcc
	s_movk_i32 s46, 0x1600
	v_readlane_b32 s34, v254, 40
	s_cbranch_execz .LBB0_111
	v_mul_u32_u24_e32 v0, 0x1600, v183
	v_lshlrev_b32_e32 v0, 1, v0
	v_cvt_pk_bf16_f32 v124, v170, v171
	v_cvt_pk_bf16_f32 v125, v172, v173
	v_lshl_add_u64 v[128:129], v[122:123], 0, v[0:1]
	v_cvt_pk_bf16_f32 v126, v158, v159
	v_cvt_pk_bf16_f32 v127, v156, v157
	global_store_dwordx2 v[128:129], v[124:125], off
	global_store_dwordx2 v[128:129], v[126:127], off offset:256

.LBB0_113:
	s_or_b64 exec, exec, s[0:1]
	v_ffbh_u32_e32 v0, v135
	v_min_u32_e32 v0, 32, v0
	v_lshlrev_b64 v[114:115], v0, v[134:135]
	v_min_u32_e32 v114, 1, v114
	v_or_b32_e32 v114, v115, v114
	v_cvt_f32_u32_e32 v114, v114
	v_sub_u32_e32 v0, 32, v0
	s_lshl_b32 s5, s78, 7
	v_add_u32_e32 v180, s5, v130
	v_ldexp_f32 v0, v114, v0
	v_mul_f32_e32 v0, 0x33800000, v0
	v_fmamk_f32 v0, v0, 0x3a800000, v210
	s_nop 0
	v_rsq_f32_e32 v0, v0
	s_nop 0
	s_nop 0
	v_mov_b32_e32 v178, v0
	v_ffbh_u32_e32 v0, v133
	v_min_u32_e32 v0, 32, v0
	v_pk_mul_f32 v[186:187], v[110:111], v[178:179] op_sel_hi:[1,0]
	v_lshlrev_b64 v[110:111], v0, v[132:133]
	v_min_u32_e32 v110, 1, v110
	v_or_b32_e32 v110, v111, v110
	v_cvt_f32_u32_e32 v110, v110
	v_sub_u32_e32 v0, 32, v0
	v_pk_mul_f32 v[184:185], v[112:113], v[178:179] op_sel_hi:[1,0]
	v_ldexp_f32 v0, v110, v0
	v_mul_f32_e32 v0, 0x33800000, v0
	v_fmamk_f32 v0, v0, 0x3a800000, v210
	s_nop 0
	v_rsq_f32_e32 v0, v0
	s_nop 0
	s_nop 0
	v_mov_b32_e32 v182, v0
	v_pk_mul_f32 v[188:189], v[108:109], v[182:183] op_sel_hi:[1,0]
	v_pk_mul_f32 v[198:199], v[106:107], v[182:183] op_sel_hi:[1,0]
	v_ashrrev_i32_e32 v181, 31, v180
	v_lshlrev_b64 v[118:119], 2, v[180:181]
	v_lshl_add_u64 v[106:107], s[44:45], 0, v[118:119]
	v_lshl_add_u64 v[108:109], s[60:61], 0, v[118:119]
	global_load_dwordx4 v[122:125], v[106:107], off
	global_load_dwordx4 v[126:129], v[108:109], off
	v_lshl_add_u64 v[106:107], s[2:3], 0, v[118:119]
	global_load_dwordx4 v[130:133], v[106:107], off
	v_lshl_add_u64 v[106:107], s[48:49], 0, v[118:119]
	global_load_dwordx4 v[134:137], v[106:107], off
	v_mov_b32_e32 v206, v1
	v_mov_b32_e32 v204, v1
	v_mov_b32_e32 v207, v1
	v_mov_b32_e32 v205, v1
	v_mov_b32_e32 v202, v1
	v_mov_b32_e32 v200, v1
	v_mov_b32_e32 v203, v1
	v_mov_b32_e32 v201, v1
	v_mov_b32_e32 v241, v1
	v_mov_b32_e32 v240, v1
	v_mov_b32_e32 v245, v1
	v_mov_b32_e32 v244, v1
	v_mov_b32_e32 v229, v1
	v_mov_b32_e32 v228, v1
	v_mov_b32_e32 v235, v1
	v_mov_b32_e32 v233, v1
	v_mov_b32_e32 v234, v1
	v_mov_b32_e32 v231, v1
	v_mov_b32_e32 v239, v1
	v_mov_b32_e32 v237, v1
	v_mov_b32_e32 v151, v1
	v_mov_b32_e32 v0, v1
	v_mov_b32_e32 v227, v1
	v_mov_b32_e32 v213, v1
	v_mov_b32_e32 v243, v1
	v_mov_b32_e32 v242, v1
	v_mov_b32_e32 v247, v1
	v_mov_b32_e32 v246, v1
	v_mov_b32_e32 v232, v1
	v_mov_b32_e32 v230, v1
	v_mov_b32_e32 v238, v1
	v_mov_b32_e32 v236, v1
	v_cmp_lt_u32_e32 vcc, 1, v183
	v_mov_b32_dpp v206, v170 row_ror:1 row_mask:0xf bank_mask:0xf
	v_mov_b32_dpp v204, v170 row_ror:2 row_mask:0xf bank_mask:0xf
	v_mov_b32_dpp v207, v171 row_ror:1 row_mask:0xf bank_mask:0xf
	v_mov_b32_dpp v205, v171 row_ror:2 row_mask:0xf bank_mask:0xf
	v_mov_b32_dpp v202, v172 row_ror:1 row_mask:0xf bank_mask:0xf
	v_mov_b32_dpp v200, v172 row_ror:2 row_mask:0xf bank_mask:0xf
	v_mov_b32_dpp v203, v173 row_ror:1 row_mask:0xf bank_mask:0xf
	v_mov_b32_dpp v201, v173 row_ror:2 row_mask:0xf bank_mask:0xf
	v_mov_b32_dpp v241, v186 row_ror:1 row_mask:0xf bank_mask:0xf
	v_mov_b32_dpp v240, v186 row_ror:2 row_mask:0xf bank_mask:0xf
	v_mov_b32_dpp v245, v187 row_ror:1 row_mask:0xf bank_mask:0xf
	v_mov_b32_dpp v244, v187 row_ror:2 row_mask:0xf bank_mask:0xf
	v_mov_b32_dpp v229, v184 row_ror:1 row_mask:0xf bank_mask:0xf
	v_mov_b32_dpp v228, v184 row_ror:2 row_mask:0xf bank_mask:0xf
	v_mov_b32_dpp v235, v185 row_ror:1 row_mask:0xf bank_mask:0xf
	v_mov_b32_dpp v233, v185 row_ror:2 row_mask:0xf bank_mask:0xf
	v_mov_b32_dpp v234, v198 row_ror:1 row_mask:0xf bank_mask:0xf
	v_mov_b32_dpp v231, v198 row_ror:2 row_mask:0xf bank_mask:0xf
	v_mov_b32_dpp v239, v199 row_ror:1 row_mask:0xf bank_mask:0xf
	v_mov_b32_dpp v237, v199 row_ror:2 row_mask:0xf bank_mask:0xf
	v_mov_b32_dpp v151, v188 row_ror:1 row_mask:0xf bank_mask:0xf
	v_mov_b32_dpp v0, v188 row_ror:2 row_mask:0xf bank_mask:0xf
	v_mov_b32_dpp v227, v189 row_ror:1 row_mask:0xf bank_mask:0xf
	v_mov_b32_dpp v213, v189 row_ror:2 row_mask:0xf bank_mask:0xf
	v_mov_b32_dpp v243, v176 row_ror:1 row_mask:0xf bank_mask:0xf
	v_mov_b32_dpp v242, v176 row_ror:2 row_mask:0xf bank_mask:0xf
	v_mov_b32_dpp v247, v177 row_ror:1 row_mask:0xf bank_mask:0xf
	v_mov_b32_dpp v246, v177 row_ror:2 row_mask:0xf bank_mask:0xf
	v_mov_b32_dpp v232, v174 row_ror:1 row_mask:0xf bank_mask:0xf
	v_mov_b32_dpp v230, v174 row_ror:2 row_mask:0xf bank_mask:0xf
	v_mov_b32_dpp v238, v175 row_ror:1 row_mask:0xf bank_mask:0xf
	v_mov_b32_dpp v236, v175 row_ror:2 row_mask:0xf bank_mask:0xf
	v_lshl_add_u64 v[106:107], s[96:97], 0, v[118:119]
	v_lshl_add_u64 v[108:109], s[62:63], 0, v[118:119]
	global_load_dwordx4 v[114:117], v[106:107], off
	global_load_dwordx4 v[110:113], v[108:109], off
	v_lshl_add_u64 v[106:107], s[64:65], 0, v[118:119]
	v_lshl_add_u64 v[118:119], s[66:67], 0, v[118:119]
	global_load_dwordx4 v[106:109], v[106:107], off
	v_mov_b32_e32 v190, v1
	global_load_dwordx4 v[118:121], v[118:119], off
	v_mov_b32_e32 v194, v1
	v_mov_b32_e32 v191, v1
	v_mov_b32_e32 v195, v1
	v_mov_b32_e32 v192, v1
	v_mov_b32_e32 v196, v1
	v_mov_b32_e32 v193, v1
	v_mov_b32_e32 v197, v1
	v_mov_b32_dpp v190, v158 row_ror:1 row_mask:0xf bank_mask:0xf
	v_mov_b32_dpp v194, v158 row_ror:2 row_mask:0xf bank_mask:0xf
	v_mov_b32_dpp v191, v159 row_ror:1 row_mask:0xf bank_mask:0xf
	v_mov_b32_dpp v195, v159 row_ror:2 row_mask:0xf bank_mask:0xf
	v_mov_b32_dpp v192, v156 row_ror:1 row_mask:0xf bank_mask:0xf
	v_mov_b32_dpp v196, v156 row_ror:2 row_mask:0xf bank_mask:0xf
	v_mov_b32_dpp v193, v157 row_ror:1 row_mask:0xf bank_mask:0xf
	v_mov_b32_dpp v197, v157 row_ror:2 row_mask:0xf bank_mask:0xf
	s_and_saveexec_b64 s[0:1], vcc
	s_mov_b32 s50, 0x20000
	s_mov_b32 s47, 0xbfb8aa3b
	s_cbranch_execz .Lcg_skip0
	s_waitcnt vmcnt(4)
	v_pk_fma_f32 v[248:249], v[124:125], v[200:201], v[136:137]
	s_nop 0
	v_pk_fma_f32 v[248:249], v[128:129], v[202:203], v[248:249]
	s_nop 0
	v_pk_fma_f32 v[172:173], v[172:173], v[132:133], v[248:249]
	v_pk_fma_f32 v[248:249], v[122:123], v[204:205], v[134:135]
	v_mul_f32_e32 v179, 0xbfb8aa3b, v173
	v_exp_f32_e32 v179, v179
	v_pk_fma_f32 v[248:249], v[126:127], v[206:207], v[248:249]
	v_mul_f32_e32 v250, 0xbfb8aa3b, v172
	v_pk_fma_f32 v[170:171], v[170:171], v[130:131], v[248:249]
	v_add_f32_e32 v179, 1.0, v179
	v_rcp_f32_e32 v251, v179
	v_mul_f32_e32 v179, 0xbfb8aa3b, v171
	v_exp_f32_e32 v179, v179
	v_mul_f32_e32 v248, 0xbfb8aa3b, v170
	v_exp_f32_e32 v250, v250
	v_exp_f32_e32 v248, v248
	v_add_f32_e32 v179, 1.0, v179
	v_rcp_f32_e32 v249, v179
	v_add_f32_e32 v250, 1.0, v250
	v_add_f32_e32 v179, 1.0, v248
	v_rcp_f32_e32 v248, v179
	v_rcp_f32_e32 v250, v250
	v_pk_mul_f32 v[170:171], v[170:171], v[248:249]
	v_pk_mul_f32 v[172:173], v[172:173], v[250:251]
	s_waitcnt vmcnt(0)
	v_pk_fma_f32 v[248:249], v[116:117], v[196:197], v[120:121]
	v_pk_fma_f32 v[250:251], v[114:115], v[194:195], v[118:119]
	v_pk_fma_f32 v[248:249], v[112:113], v[192:193], v[248:249]
	v_pk_fma_f32 v[250:251], v[110:111], v[190:191], v[250:251]
	v_pk_fma_f32 v[156:157], v[156:157], v[108:109], v[248:249]
	v_pk_fma_f32 v[158:159], v[158:159], v[106:107], v[250:251]
	v_pk_mul_f32 v[156:157], v[172:173], v[156:157]
	v_pk_mul_f32 v[158:159], v[170:171], v[158:159]
	s_nop 0
	v_cvt_pk_bf16_f32 v158, v158, v159
	v_cvt_pk_bf16_f32 v159, v156, v157
	v_mov_b64_e32 v[156:157], s[36:37]
	v_mad_i64_i32 v[156:157], s[28:29], v150, s46, v[156:157]
	v_lshl_add_u64 v[156:157], v[180:181], 1, v[156:157]
	global_store_dwordx2 v[156:157], v[158:159], off
.LBB0_115:
	s_or_b64 exec, exec, s[0:1]
	v_cmp_eq_u32_e64 s[42:43], 0, v183
	v_cndmask_b32_e32 v159, v205, v244, vcc
	v_cndmask_b32_e32 v158, v204, v240, vcc
	v_cndmask_b32_e64 v157, v245, v207, s[42:43]
	v_cndmask_b32_e64 v156, v241, v206, s[42:43]
	s_waitcnt vmcnt(4)
	v_pk_fma_f32 v[158:159], v[122:123], v[158:159], v[134:135]
	v_cndmask_b32_e32 v173, v201, v233, vcc
	v_cndmask_b32_e32 v172, v200, v228, vcc
	v_pk_fma_f32 v[156:157], v[126:127], v[156:157], v[158:159]
	v_cndmask_b32_e64 v171, v235, v203, s[42:43]
	v_cndmask_b32_e64 v170, v229, v202, s[42:43]
	v_pk_fma_f32 v[172:173], v[124:125], v[172:173], v[136:137]
	v_pk_fma_f32 v[156:157], v[186:187], v[130:131], v[156:157]
	v_pk_fma_f32 v[170:171], v[128:129], v[170:171], v[172:173]
	v_cndmask_b32_e32 v187, v244, v237, vcc
	v_cndmask_b32_e32 v186, v240, v231, vcc
	v_pk_fma_f32 v[170:171], v[184:185], v[132:133], v[170:171]
	v_cndmask_b32_e64 v185, v239, v245, s[42:43]
	v_cndmask_b32_e64 v184, v234, v241, s[42:43]
	v_pk_fma_f32 v[186:187], v[122:123], v[186:187], v[134:135]
	v_cndmask_b32_e32 v201, v233, v213, vcc
	v_pk_fma_f32 v[184:185], v[126:127], v[184:185], v[186:187]
	v_cndmask_b32_e32 v200, v228, v0, vcc
	v_pk_fma_f32 v[184:185], v[198:199], v[130:131], v[184:185]
	v_cndmask_b32_e64 v199, v227, v235, s[42:43]
	v_cndmask_b32_e64 v198, v151, v229, s[42:43]
	v_pk_fma_f32 v[200:201], v[124:125], v[200:201], v[136:137]
	v_cndmask_b32_e32 v203, v237, v246, vcc
	v_cndmask_b32_e32 v202, v231, v242, vcc
	v_pk_fma_f32 v[198:199], v[128:129], v[198:199], v[200:201]
	v_cndmask_b32_e64 v201, v247, v239, s[42:43]
	v_cndmask_b32_e64 v200, v243, v234, s[42:43]
	v_pk_fma_f32 v[122:123], v[122:123], v[202:203], v[134:135]
	v_cndmask_b32_e32 v135, v213, v236, vcc
	v_pk_fma_f32 v[122:123], v[126:127], v[200:201], v[122:123]
	v_cndmask_b32_e32 v134, v0, v230, vcc
	v_mul_f32_e32 v158, 0xbfb8aa3b, v156
	v_mul_f32_e32 v159, 0xbfb8aa3b, v157
	v_mul_f32_e32 v172, 0xbfb8aa3b, v170
	v_mul_f32_e32 v173, 0xbfb8aa3b, v171
	v_pk_fma_f32 v[122:123], v[176:177], v[130:131], v[122:123]
	v_cndmask_b32_e64 v131, v238, v227, s[42:43]
	v_cndmask_b32_e64 v130, v232, v151, s[42:43]
	v_pk_fma_f32 v[124:125], v[124:125], v[134:135], v[136:137]
	v_exp_f32_e32 v158, v158
	v_exp_f32_e32 v159, v159
	v_exp_f32_e32 v172, v172
	v_exp_f32_e32 v173, v173
	v_pk_fma_f32 v[124:125], v[128:129], v[130:131], v[124:125]
	v_mov_b32_e32 v179, v178
	v_pk_fma_f32 v[124:125], v[174:175], v[132:133], v[124:125]
	v_mov_b32_e32 v183, v182
	v_mul_f32_e32 v0, 0xbfb8aa3b, v124
	v_exp_f32_e32 v0, v0
	v_mul_f32_e32 v128, 0xbfb8aa3b, v125
	v_mov_b32_e32 v130, v178
	v_mov_b32_e32 v131, v178
	v_add_f32_e32 v158, 1.0, v158
	v_add_f32_e32 v159, 1.0, v159
	v_add_f32_e32 v172, 1.0, v172
	v_add_f32_e32 v173, 1.0, v173
	v_exp_f32_e32 v129, v128
	v_pk_mul_f32 v[104:105], v[104:105], v[130:131]
	v_pk_mul_f32 v[102:103], v[102:103], v[178:179]
	v_pk_mul_f32 v[98:99], v[98:99], v[182:183]
	v_mov_b32_e32 v177, v1
	v_mov_b32_e32 v179, v1
	v_mov_b32_e32 v183, v1
	v_mov_b32_e32 v201, v1
	v_rcp_f32_e32 v158, v158
	v_rcp_f32_e32 v159, v159
	v_rcp_f32_e32 v172, v172
	v_rcp_f32_e32 v173, v173
	v_mov_b32_e32 v130, v182
	v_mov_b32_e32 v131, v182
	v_mov_b32_e32 v176, v1
	v_mov_b32_dpp v177, v102 row_ror:2 row_mask:0xf bank_mask:0xf
	v_mov_b32_e32 v178, v1
	v_mov_b32_dpp v179, v103 row_ror:2 row_mask:0xf bank_mask:0xf
	v_mov_b32_e32 v182, v1
	v_mov_b32_dpp v183, v104 row_ror:2 row_mask:0xf bank_mask:0xf
	v_mov_b32_e32 v200, v1
	v_mov_b32_dpp v201, v105 row_ror:2 row_mask:0xf bank_mask:0xf
	v_pk_fma_f32 v[188:189], v[188:189], v[132:133], v[198:199]
	v_pk_mul_f32 v[100:101], v[100:101], v[130:131]
	v_mov_b32_dpp v176, v102 row_ror:1 row_mask:0xf bank_mask:0xf
	v_mov_b32_dpp v178, v103 row_ror:1 row_mask:0xf bank_mask:0xf
	v_mov_b32_dpp v182, v104 row_ror:1 row_mask:0xf bank_mask:0xf
	v_mov_b32_dpp v200, v105 row_ror:1 row_mask:0xf bank_mask:0xf
	v_cndmask_b32_e32 v130, v194, v177, vcc
	v_cndmask_b32_e32 v131, v195, v179, vcc
	v_cndmask_b32_e32 v132, v196, v183, vcc
	v_cndmask_b32_e32 v133, v197, v201, vcc
	v_mul_f32_e32 v186, 0xbfb8aa3b, v184
	v_mul_f32_e32 v187, 0xbfb8aa3b, v185
	v_mul_f32_e32 v198, 0xbfb8aa3b, v188
	v_mul_f32_e32 v199, 0xbfb8aa3b, v189
	v_add_f32_e32 v0, 1.0, v0
	v_cndmask_b32_e64 v134, v176, v190, s[42:43]
	v_cndmask_b32_e64 v135, v178, v191, s[42:43]
	v_cndmask_b32_e64 v136, v182, v192, s[42:43]
	v_cndmask_b32_e64 v137, v200, v193, s[42:43]
	s_waitcnt vmcnt(1)
	v_pk_fma_f32 v[132:133], v[116:117], v[132:133], v[120:121]
	v_pk_fma_f32 v[130:131], v[114:115], v[130:131], v[118:119]
	v_exp_f32_e32 v186, v186
	v_exp_f32_e32 v187, v187
	v_exp_f32_e32 v198, v198
	v_exp_f32_e32 v199, v199
	v_rcp_f32_e32 v128, v0
	v_add_f32_e32 v0, 1.0, v129
	v_pk_fma_f32 v[132:133], v[112:113], v[136:137], v[132:133]
	v_pk_fma_f32 v[130:131], v[110:111], v[134:135], v[130:131]
	v_rcp_f32_e32 v129, v0
	v_or_b32_e32 v0, 16, v150
	v_or_b32_e32 v174, 32, v150
	v_or_b32_e32 v175, 48, v150
	v_pk_mul_f32 v[150:151], v[156:157], v[158:159]
	v_pk_mul_f32 v[156:157], v[170:171], v[172:173]
	v_pk_fma_f32 v[104:105], v[104:105], v[108:109], v[132:133]
	v_pk_fma_f32 v[102:103], v[102:103], v[106:107], v[130:131]
	v_pk_mul_f32 v[104:105], v[156:157], v[104:105]
	v_pk_mul_f32 v[102:103], v[150:151], v[102:103]
	v_add_f32_e32 v186, 1.0, v186
	v_cvt_pk_bf16_f32 v102, v102, v103
	v_cvt_pk_bf16_f32 v103, v104, v105
	v_mov_b64_e32 v[104:105], s[36:37]
	v_add_f32_e32 v187, 1.0, v187
	v_add_f32_e32 v198, 1.0, v198
	v_add_f32_e32 v199, 1.0, v199
	v_mad_i64_i32 v[130:131], s[0:1], v0, s46, v[104:105]
	v_lshlrev_b64 v[132:133], 1, v[180:181]
	v_mov_b32_e32 v158, v1
	v_mov_b32_e32 v170, v1
	v_mov_b32_e32 v172, v1
	v_mov_b32_e32 v180, v1
	v_rcp_f32_e32 v186, v186
	v_rcp_f32_e32 v187, v187
	v_rcp_f32_e32 v198, v198
	v_rcp_f32_e32 v199, v199
	v_lshl_add_u64 v[130:131], v[130:131], 0, v[132:133]
	v_mov_b32_e32 v0, v1
	v_mov_b32_dpp v158, v98 row_ror:2 row_mask:0xf bank_mask:0xf
	v_mov_b32_e32 v159, v1
	v_mov_b32_dpp v170, v99 row_ror:2 row_mask:0xf bank_mask:0xf
	v_mov_b32_e32 v171, v1
	v_mov_b32_dpp v172, v100 row_ror:2 row_mask:0xf bank_mask:0xf
	v_mov_b32_e32 v173, v1
	v_mov_b32_dpp v180, v101 row_ror:2 row_mask:0xf bank_mask:0xf
	global_store_dwordx2 v[130:131], v[102:103], off
	v_mov_b32_dpp v0, v98 row_ror:1 row_mask:0xf bank_mask:0xf
	v_mov_b32_dpp v159, v99 row_ror:1 row_mask:0xf bank_mask:0xf
	v_mov_b32_dpp v171, v100 row_ror:1 row_mask:0xf bank_mask:0xf
	v_mov_b32_dpp v173, v101 row_ror:1 row_mask:0xf bank_mask:0xf
	v_cndmask_b32_e32 v102, v177, v158, vcc
	v_cndmask_b32_e32 v103, v179, v170, vcc
	v_cndmask_b32_e32 v130, v183, v172, vcc
	v_cndmask_b32_e32 v131, v201, v180, vcc
	v_cndmask_b32_e64 v134, v0, v176, s[42:43]
	v_cndmask_b32_e64 v135, v159, v178, s[42:43]
	v_cndmask_b32_e64 v136, v171, v182, s[42:43]
	v_cndmask_b32_e64 v137, v173, v200, s[42:43]
	v_pk_fma_f32 v[130:131], v[116:117], v[130:131], v[120:121]
	v_pk_fma_f32 v[102:103], v[114:115], v[102:103], v[118:119]
	v_mul_f32_e32 v126, 0xbfb8aa3b, v122
	v_mul_f32_e32 v127, 0xbfb8aa3b, v123
	v_pk_fma_f32 v[130:131], v[112:113], v[136:137], v[130:131]
	v_pk_fma_f32 v[102:103], v[110:111], v[134:135], v[102:103]
	v_exp_f32_e32 v126, v126
	v_exp_f32_e32 v127, v127
	v_pk_mul_f32 v[150:151], v[184:185], v[186:187]
	v_pk_mul_f32 v[156:157], v[188:189], v[198:199]
	v_pk_fma_f32 v[100:101], v[100:101], v[108:109], v[130:131]
	v_pk_fma_f32 v[98:99], v[98:99], v[106:107], v[102:103]
	v_pk_mul_f32 v[100:101], v[156:157], v[100:101]
	v_pk_mul_f32 v[98:99], v[150:151], v[98:99]
	v_add_f32_e32 v126, 1.0, v126
	v_cvt_pk_bf16_f32 v98, v98, v99
	v_cvt_pk_bf16_f32 v99, v100, v101
	v_mad_i64_i32 v[100:101], s[0:1], v174, s46, v[104:105]
	v_lshl_add_u64 v[100:101], v[100:101], 0, v[132:133]
	v_add_f32_e32 v127, 1.0, v127
	global_store_dwordx2 v[100:101], v[98:99], off
	v_mov_b32_e32 v98, v1
	v_mov_b32_e32 v99, v1
	v_mov_b32_e32 v100, v1
	v_mov_b32_e32 v101, v1
	v_rcp_f32_e32 v126, v126
	v_rcp_f32_e32 v127, v127
	v_mov_b32_e32 v102, v1
	v_mov_b32_dpp v98, v154 row_ror:2 row_mask:0xf bank_mask:0xf
	v_mov_b32_e32 v103, v1
	v_mov_b32_dpp v99, v155 row_ror:2 row_mask:0xf bank_mask:0xf
	v_mov_b32_e32 v130, v1
	v_mov_b32_dpp v100, v152 row_ror:2 row_mask:0xf bank_mask:0xf
	v_mov_b32_e32 v131, v1
	v_mov_b32_dpp v101, v153 row_ror:2 row_mask:0xf bank_mask:0xf
	v_mov_b32_dpp v102, v154 row_ror:1 row_mask:0xf bank_mask:0xf
	v_mov_b32_dpp v103, v155 row_ror:1 row_mask:0xf bank_mask:0xf
	v_mov_b32_dpp v130, v152 row_ror:1 row_mask:0xf bank_mask:0xf
	v_mov_b32_dpp v131, v153 row_ror:1 row_mask:0xf bank_mask:0xf
	v_cndmask_b32_e32 v98, v158, v98, vcc
	v_cndmask_b32_e32 v99, v170, v99, vcc
	v_cndmask_b32_e32 v100, v172, v100, vcc
	v_cndmask_b32_e32 v101, v180, v101, vcc
	v_cndmask_b32_e64 v102, v102, v0, s[42:43]
	v_cndmask_b32_e64 v103, v103, v159, s[42:43]
	v_cndmask_b32_e64 v130, v130, v171, s[42:43]
	v_cndmask_b32_e64 v131, v131, v173, s[42:43]
	v_pk_fma_f32 v[98:99], v[114:115], v[98:99], v[118:119]
	v_pk_fma_f32 v[100:101], v[116:117], v[100:101], v[120:121]
	v_pk_fma_f32 v[98:99], v[110:111], v[102:103], v[98:99]
	v_pk_fma_f32 v[100:101], v[112:113], v[130:131], v[100:101]
	v_pk_mul_f32 v[122:123], v[122:123], v[126:127]
	v_pk_mul_f32 v[124:125], v[124:125], v[128:129]
	v_pk_fma_f32 v[98:99], v[154:155], v[106:107], v[98:99]
	v_pk_fma_f32 v[100:101], v[152:153], v[108:109], v[100:101]
	v_pk_mul_f32 v[98:99], v[122:123], v[98:99]
	v_pk_mul_f32 v[100:101], v[124:125], v[100:101]
	v_cvt_pk_bf16_f32 v98, v98, v99
	s_nop 0
	v_cvt_pk_bf16_f32 v99, v100, v101
	v_mad_i64_i32 v[100:101], s[0:1], v175, s46, v[104:105]
	v_lshl_add_u64 v[100:101], v[100:101], 0, v[132:133]
	global_store_dwordx2 v[100:101], v[98:99], off
	s_add_i32 s0, s6, 2
	v_and_b32_e32 v129, 15, v226
	v_or_b32_e32 v106, s4, v129
	v_ashrrev_i32_e32 v107, 31, v106
	v_lshl_add_u64 v[104:105], v[106:107], 3, s[38:39]
	global_load_dwordx2 v[108:109], v[104:105], off offset:1024
	global_load_dwordx2 v[102:103], v[104:105], off offset:1152
	global_load_dwordx2 v[100:101], v[104:105], off offset:1280
	s_nop 0
	global_load_dwordx2 v[104:105], v[104:105], off offset:1408
	v_ashrrev_i32_e32 v0, 1, v226
	v_and_b32_e32 v0, -8, v0
	v_add_u32_e32 v98, s21, v0
	s_mul_hi_i32 s1, s0, 0xb000
	s_mul_i32 s0, s0, 0xb000
	s_add_u32 s0, s18, s0
	s_addc_u32 s1, s19, s1
	s_add_u32 s78, s0, s80
	s_addc_u32 s79, s1, s81
	s_waitcnt vmcnt(3)
	v_ffbh_u32_e32 v0, v109
	v_min_u32_e32 v0, 32, v0
	v_lshlrev_b64 v[108:109], v0, v[108:109]
	v_min_u32_e32 v99, 1, v108
	v_or_b32_e32 v99, v109, v99
	v_cvt_f32_u32_e32 v99, v99
	v_sub_u32_e32 v0, 32, v0
	v_ldexp_f32 v0, v99, v0
	v_mul_f32_e32 v0, 0x33800000, v0
	v_fmamk_f32 v0, v0, 0x3a800000, v210
	s_nop 0
	v_rsq_f32_e32 v0, v0
	s_nop 0
	s_nop 0
	v_ashrrev_i32_e32 v99, 31, v98
	v_pk_mul_f32 v[118:119], v[96:97], v[0:1] op_sel_hi:[1,0]
	v_pk_mul_f32 v[116:117], v[94:95], v[0:1] op_sel_hi:[1,0]
	v_pk_mul_f32 v[112:113], v[92:93], v[0:1] op_sel_hi:[1,0]
	v_pk_mul_f32 v[114:115], v[90:91], v[0:1] op_sel_hi:[1,0]
	v_lshl_add_u64 v[90:91], v[98:99], 1, s[78:79]
	v_cmp_gt_u32_e32 vcc, 2, v129
	s_and_saveexec_b64 s[0:1], vcc
	s_cbranch_execz .LBB0_117
	v_mul_u32_u24_e32 v0, 0x1600, v129
	v_lshlrev_b32_e32 v0, 1, v0
	v_cvt_pk_bf16_f32 v92, v116, v117
	v_cvt_pk_bf16_f32 v93, v118, v119
	v_lshl_add_u64 v[96:97], v[90:91], 0, v[0:1]
	v_cvt_pk_bf16_f32 v94, v114, v115
	v_cvt_pk_bf16_f32 v95, v112, v113
	global_store_dwordx2 v[96:97], v[92:93], off
	global_store_dwordx2 v[96:97], v[94:95], off offset:256

.LBB0_119:
	s_or_b64 exec, exec, s[0:1]
	v_ffbh_u32_e32 v0, v103
	v_min_u32_e32 v0, 32, v0
	v_lshlrev_b64 v[82:83], v0, v[102:103]
	v_min_u32_e32 v82, 1, v82
	v_or_b32_e32 v82, v83, v82
	v_cvt_f32_u32_e32 v82, v82
	v_sub_u32_e32 v0, 32, v0
	v_add_u32_e32 v126, s5, v98
	v_ldexp_f32 v0, v82, v0
	v_mul_f32_e32 v0, 0x33800000, v0
	v_fmamk_f32 v0, v0, 0x3a800000, v210
	s_nop 0
	v_rsq_f32_e32 v0, v0
	s_nop 0
	s_nop 0
	v_mov_b32_e32 v124, v0
	v_ffbh_u32_e32 v0, v101
	v_min_u32_e32 v0, 32, v0
	v_pk_mul_f32 v[132:133], v[78:79], v[124:125] op_sel_hi:[1,0]
	v_lshlrev_b64 v[78:79], v0, v[100:101]
	v_min_u32_e32 v78, 1, v78
	v_or_b32_e32 v78, v79, v78
	v_cvt_f32_u32_e32 v78, v78
	v_sub_u32_e32 v0, 32, v0
	v_pk_mul_f32 v[130:131], v[80:81], v[124:125] op_sel_hi:[1,0]
	v_ldexp_f32 v0, v78, v0
	v_mul_f32_e32 v0, 0x33800000, v0
	v_fmamk_f32 v0, v0, 0x3a800000, v210
	s_nop 0
	v_rsq_f32_e32 v0, v0
	s_nop 0
	s_nop 0
	v_mov_b32_e32 v128, v0
	v_pk_mul_f32 v[134:135], v[76:77], v[128:129] op_sel_hi:[1,0]
	v_pk_mul_f32 v[156:157], v[74:75], v[128:129] op_sel_hi:[1,0]
	v_ashrrev_i32_e32 v127, 31, v126
	v_lshlrev_b64 v[86:87], 2, v[126:127]
	v_lshl_add_u64 v[74:75], s[44:45], 0, v[86:87]
	v_lshl_add_u64 v[76:77], s[60:61], 0, v[86:87]
	global_load_dwordx4 v[90:93], v[74:75], off
	global_load_dwordx4 v[94:97], v[76:77], off
	v_lshl_add_u64 v[74:75], s[2:3], 0, v[86:87]
	global_load_dwordx4 v[98:101], v[74:75], off
	v_lshl_add_u64 v[74:75], s[48:49], 0, v[86:87]
	global_load_dwordx4 v[102:105], v[74:75], off
	v_mov_b32_e32 v174, v1
	v_mov_b32_e32 v172, v1
	v_mov_b32_e32 v175, v1
	v_mov_b32_e32 v173, v1
	v_mov_b32_e32 v170, v1
	v_mov_b32_e32 v158, v1
	v_mov_b32_e32 v171, v1
	v_mov_b32_e32 v159, v1
	v_mov_b32_e32 v191, v1
	v_mov_b32_e32 v190, v1
	v_mov_b32_e32 v195, v1
	v_mov_b32_e32 v194, v1
	v_mov_b32_e32 v179, v1
	v_mov_b32_e32 v178, v1
	v_mov_b32_e32 v185, v1
	v_mov_b32_e32 v183, v1
	v_mov_b32_e32 v184, v1
	v_mov_b32_e32 v181, v1
	v_mov_b32_e32 v189, v1
	v_mov_b32_e32 v187, v1
	v_mov_b32_e32 v107, v1
	v_mov_b32_e32 v0, v1
	v_mov_b32_e32 v177, v1
	v_mov_b32_e32 v176, v1
	v_mov_b32_e32 v193, v1
	v_mov_b32_e32 v192, v1
	v_mov_b32_e32 v197, v1
	v_mov_b32_e32 v196, v1
	v_mov_b32_e32 v182, v1
	v_mov_b32_e32 v180, v1
	v_mov_b32_e32 v188, v1
	v_mov_b32_e32 v186, v1
	v_cmp_lt_u32_e32 vcc, 1, v129
	v_mov_b32_dpp v174, v116 row_ror:1 row_mask:0xf bank_mask:0xf
	v_mov_b32_dpp v172, v116 row_ror:2 row_mask:0xf bank_mask:0xf
	v_mov_b32_dpp v175, v117 row_ror:1 row_mask:0xf bank_mask:0xf
	v_mov_b32_dpp v173, v117 row_ror:2 row_mask:0xf bank_mask:0xf
	v_mov_b32_dpp v170, v118 row_ror:1 row_mask:0xf bank_mask:0xf
	v_mov_b32_dpp v158, v118 row_ror:2 row_mask:0xf bank_mask:0xf
	v_mov_b32_dpp v171, v119 row_ror:1 row_mask:0xf bank_mask:0xf
	v_mov_b32_dpp v159, v119 row_ror:2 row_mask:0xf bank_mask:0xf
	v_mov_b32_dpp v191, v132 row_ror:1 row_mask:0xf bank_mask:0xf
	v_mov_b32_dpp v190, v132 row_ror:2 row_mask:0xf bank_mask:0xf
	v_mov_b32_dpp v195, v133 row_ror:1 row_mask:0xf bank_mask:0xf
	v_mov_b32_dpp v194, v133 row_ror:2 row_mask:0xf bank_mask:0xf
	v_mov_b32_dpp v179, v130 row_ror:1 row_mask:0xf bank_mask:0xf
	v_mov_b32_dpp v178, v130 row_ror:2 row_mask:0xf bank_mask:0xf
	v_mov_b32_dpp v185, v131 row_ror:1 row_mask:0xf bank_mask:0xf
	v_mov_b32_dpp v183, v131 row_ror:2 row_mask:0xf bank_mask:0xf
	v_mov_b32_dpp v184, v156 row_ror:1 row_mask:0xf bank_mask:0xf
	v_mov_b32_dpp v181, v156 row_ror:2 row_mask:0xf bank_mask:0xf
	v_mov_b32_dpp v189, v157 row_ror:1 row_mask:0xf bank_mask:0xf
	v_mov_b32_dpp v187, v157 row_ror:2 row_mask:0xf bank_mask:0xf
	v_mov_b32_dpp v107, v134 row_ror:1 row_mask:0xf bank_mask:0xf
	v_mov_b32_dpp v0, v134 row_ror:2 row_mask:0xf bank_mask:0xf
	v_mov_b32_dpp v177, v135 row_ror:1 row_mask:0xf bank_mask:0xf
	v_mov_b32_dpp v176, v135 row_ror:2 row_mask:0xf bank_mask:0xf
	v_mov_b32_dpp v193, v122 row_ror:1 row_mask:0xf bank_mask:0xf
	v_mov_b32_dpp v192, v122 row_ror:2 row_mask:0xf bank_mask:0xf
	v_mov_b32_dpp v197, v123 row_ror:1 row_mask:0xf bank_mask:0xf
	v_mov_b32_dpp v196, v123 row_ror:2 row_mask:0xf bank_mask:0xf
	v_mov_b32_dpp v182, v120 row_ror:1 row_mask:0xf bank_mask:0xf
	v_mov_b32_dpp v180, v120 row_ror:2 row_mask:0xf bank_mask:0xf
	v_mov_b32_dpp v188, v121 row_ror:1 row_mask:0xf bank_mask:0xf
	v_mov_b32_dpp v186, v121 row_ror:2 row_mask:0xf bank_mask:0xf
	v_lshl_add_u64 v[74:75], s[96:97], 0, v[86:87]
	v_lshl_add_u64 v[76:77], s[62:63], 0, v[86:87]
	global_load_dwordx4 v[82:85], v[74:75], off
	global_load_dwordx4 v[78:81], v[76:77], off
	v_lshl_add_u64 v[74:75], s[64:65], 0, v[86:87]
	v_lshl_add_u64 v[86:87], s[66:67], 0, v[86:87]
	global_load_dwordx4 v[74:77], v[74:75], off
	v_mov_b32_e32 v136, v1
	global_load_dwordx4 v[86:89], v[86:87], off
	v_mov_b32_e32 v152, v1
	v_mov_b32_e32 v137, v1
	v_mov_b32_e32 v153, v1
	v_mov_b32_e32 v150, v1
	v_mov_b32_e32 v154, v1
	v_mov_b32_e32 v151, v1
	v_mov_b32_e32 v155, v1
	v_mov_b32_dpp v136, v114 row_ror:1 row_mask:0xf bank_mask:0xf
	v_mov_b32_dpp v152, v114 row_ror:2 row_mask:0xf bank_mask:0xf
	v_mov_b32_dpp v137, v115 row_ror:1 row_mask:0xf bank_mask:0xf
	v_mov_b32_dpp v153, v115 row_ror:2 row_mask:0xf bank_mask:0xf
	v_mov_b32_dpp v150, v112 row_ror:1 row_mask:0xf bank_mask:0xf
	v_mov_b32_dpp v154, v112 row_ror:2 row_mask:0xf bank_mask:0xf
	v_mov_b32_dpp v151, v113 row_ror:1 row_mask:0xf bank_mask:0xf
	v_mov_b32_dpp v155, v113 row_ror:2 row_mask:0xf bank_mask:0xf
	s_and_saveexec_b64 s[0:1], vcc
	s_cbranch_execz .Lcg_skip1
	s_waitcnt vmcnt(4)
	v_pk_fma_f32 v[198:199], v[92:93], v[158:159], v[104:105]
	s_nop 0
	v_pk_fma_f32 v[198:199], v[96:97], v[170:171], v[198:199]
	s_nop 0
	v_pk_fma_f32 v[118:119], v[118:119], v[100:101], v[198:199]
	v_pk_fma_f32 v[198:199], v[90:91], v[172:173], v[102:103]
	v_mul_f32_e32 v125, 0xbfb8aa3b, v119
	v_exp_f32_e32 v125, v125
	v_pk_fma_f32 v[198:199], v[94:95], v[174:175], v[198:199]
	v_mul_f32_e32 v200, 0xbfb8aa3b, v118
	v_pk_fma_f32 v[116:117], v[116:117], v[98:99], v[198:199]
	v_add_f32_e32 v125, 1.0, v125
	v_rcp_f32_e32 v201, v125
	v_mul_f32_e32 v125, 0xbfb8aa3b, v117
	v_exp_f32_e32 v125, v125
	v_mul_f32_e32 v198, 0xbfb8aa3b, v116
	v_exp_f32_e32 v200, v200
	v_exp_f32_e32 v198, v198
	v_add_f32_e32 v125, 1.0, v125
	v_rcp_f32_e32 v199, v125
	v_add_f32_e32 v200, 1.0, v200
	v_add_f32_e32 v125, 1.0, v198
	v_rcp_f32_e32 v198, v125
	v_rcp_f32_e32 v200, v200
	v_add_u32_e32 v125, 0x80, v106
	v_pk_mul_f32 v[116:117], v[116:117], v[198:199]
	v_pk_mul_f32 v[118:119], v[118:119], v[200:201]
	s_waitcnt vmcnt(0)
	v_pk_fma_f32 v[198:199], v[84:85], v[154:155], v[88:89]
	v_pk_fma_f32 v[200:201], v[82:83], v[152:153], v[86:87]
	v_pk_fma_f32 v[198:199], v[80:81], v[150:151], v[198:199]
	v_pk_fma_f32 v[200:201], v[78:79], v[136:137], v[200:201]
	v_pk_fma_f32 v[112:113], v[112:113], v[76:77], v[198:199]
	v_pk_fma_f32 v[114:115], v[114:115], v[74:75], v[200:201]
	v_pk_mul_f32 v[112:113], v[118:119], v[112:113]
	v_pk_mul_f32 v[114:115], v[116:117], v[114:115]
	s_nop 0
	v_cvt_pk_bf16_f32 v114, v114, v115
	v_cvt_pk_bf16_f32 v115, v112, v113
	v_mov_b64_e32 v[112:113], s[36:37]
	v_mad_i64_i32 v[112:113], s[6:7], v125, s46, v[112:113]
	v_lshl_add_u64 v[112:113], v[126:127], 1, v[112:113]
	global_store_dwordx2 v[112:113], v[114:115], off
.LBB0_121:
	s_or_b64 exec, exec, s[0:1]
	v_cmp_eq_u32_e64 s[42:43], 0, v129
	v_cndmask_b32_e32 v115, v173, v194, vcc
	v_cndmask_b32_e32 v114, v172, v190, vcc
	v_cndmask_b32_e64 v113, v195, v175, s[42:43]
	v_cndmask_b32_e64 v112, v191, v174, s[42:43]
	s_waitcnt vmcnt(4)
	v_pk_fma_f32 v[114:115], v[90:91], v[114:115], v[102:103]
	v_cndmask_b32_e32 v119, v159, v183, vcc
	v_cndmask_b32_e32 v118, v158, v178, vcc
	v_pk_fma_f32 v[112:113], v[94:95], v[112:113], v[114:115]
	v_cndmask_b32_e64 v117, v185, v171, s[42:43]
	v_cndmask_b32_e64 v116, v179, v170, s[42:43]
	v_pk_fma_f32 v[118:119], v[92:93], v[118:119], v[104:105]
	v_pk_fma_f32 v[112:113], v[132:133], v[98:99], v[112:113]
	v_pk_fma_f32 v[116:117], v[96:97], v[116:117], v[118:119]
	v_cndmask_b32_e32 v133, v194, v187, vcc
	v_cndmask_b32_e32 v132, v190, v181, vcc
	v_pk_fma_f32 v[116:117], v[130:131], v[100:101], v[116:117]
	v_cndmask_b32_e64 v131, v189, v195, s[42:43]
	v_cndmask_b32_e64 v130, v184, v191, s[42:43]
	v_pk_fma_f32 v[132:133], v[90:91], v[132:133], v[102:103]
	v_cndmask_b32_e32 v159, v183, v176, vcc
	v_pk_fma_f32 v[130:131], v[94:95], v[130:131], v[132:133]
	v_cndmask_b32_e32 v158, v178, v0, vcc
	v_pk_fma_f32 v[130:131], v[156:157], v[98:99], v[130:131]
	v_cndmask_b32_e64 v157, v177, v185, s[42:43]
	v_cndmask_b32_e64 v156, v107, v179, s[42:43]
	v_pk_fma_f32 v[158:159], v[92:93], v[158:159], v[104:105]
	v_cndmask_b32_e32 v171, v187, v196, vcc
	v_cndmask_b32_e32 v170, v181, v192, vcc
	v_pk_fma_f32 v[156:157], v[96:97], v[156:157], v[158:159]
	v_cndmask_b32_e64 v159, v197, v189, s[42:43]
	v_cndmask_b32_e64 v158, v193, v184, s[42:43]
	v_pk_fma_f32 v[90:91], v[90:91], v[170:171], v[102:103]
	v_cndmask_b32_e32 v103, v176, v186, vcc
	v_pk_fma_f32 v[90:91], v[94:95], v[158:159], v[90:91]
	v_cndmask_b32_e32 v102, v0, v180, vcc
	v_mul_f32_e32 v114, 0xbfb8aa3b, v112
	v_mul_f32_e32 v115, 0xbfb8aa3b, v113
	v_mul_f32_e32 v118, 0xbfb8aa3b, v116
	v_mul_f32_e32 v119, 0xbfb8aa3b, v117
	v_pk_fma_f32 v[90:91], v[122:123], v[98:99], v[90:91]
	v_cndmask_b32_e64 v99, v188, v177, s[42:43]
	v_cndmask_b32_e64 v98, v182, v107, s[42:43]
	v_pk_fma_f32 v[92:93], v[92:93], v[102:103], v[104:105]
	v_exp_f32_e32 v114, v114
	v_exp_f32_e32 v115, v115
	v_exp_f32_e32 v118, v118
	v_exp_f32_e32 v119, v119
	v_pk_fma_f32 v[92:93], v[96:97], v[98:99], v[92:93]
	v_mov_b32_e32 v125, v124
	v_pk_fma_f32 v[92:93], v[120:121], v[100:101], v[92:93]
	v_mov_b32_e32 v129, v128
	v_mul_f32_e32 v0, 0xbfb8aa3b, v92
	v_exp_f32_e32 v0, v0
	v_mul_f32_e32 v96, 0xbfb8aa3b, v93
	v_mov_b32_e32 v98, v124
	v_mov_b32_e32 v99, v124
	v_add_f32_e32 v114, 1.0, v114
	v_add_f32_e32 v115, 1.0, v115
	v_add_f32_e32 v118, 1.0, v118
	v_add_f32_e32 v119, 1.0, v119
	v_exp_f32_e32 v97, v96
	v_pk_mul_f32 v[72:73], v[72:73], v[98:99]
	v_pk_mul_f32 v[70:71], v[70:71], v[124:125]
	v_pk_mul_f32 v[66:67], v[66:67], v[128:129]
	v_mov_b32_e32 v123, v1
	v_mov_b32_e32 v125, v1
	v_mov_b32_e32 v129, v1
	v_mov_b32_e32 v159, v1
	v_rcp_f32_e32 v114, v114
	v_rcp_f32_e32 v115, v115
	v_rcp_f32_e32 v118, v118
	v_rcp_f32_e32 v119, v119
	v_mov_b32_e32 v98, v128
	v_mov_b32_e32 v99, v128
	v_mov_b32_e32 v122, v1
	v_mov_b32_dpp v123, v70 row_ror:2 row_mask:0xf bank_mask:0xf
	v_mov_b32_e32 v124, v1
	v_mov_b32_dpp v125, v71 row_ror:2 row_mask:0xf bank_mask:0xf
	v_mov_b32_e32 v128, v1
	v_mov_b32_dpp v129, v72 row_ror:2 row_mask:0xf bank_mask:0xf
	v_mov_b32_e32 v158, v1
	v_mov_b32_dpp v159, v73 row_ror:2 row_mask:0xf bank_mask:0xf
	v_pk_fma_f32 v[134:135], v[134:135], v[100:101], v[156:157]
	v_pk_mul_f32 v[68:69], v[68:69], v[98:99]
	v_mov_b32_dpp v122, v70 row_ror:1 row_mask:0xf bank_mask:0xf
	v_mov_b32_dpp v124, v71 row_ror:1 row_mask:0xf bank_mask:0xf
	v_mov_b32_dpp v128, v72 row_ror:1 row_mask:0xf bank_mask:0xf
	v_mov_b32_dpp v158, v73 row_ror:1 row_mask:0xf bank_mask:0xf
	v_cndmask_b32_e32 v98, v152, v123, vcc
	v_cndmask_b32_e32 v99, v153, v125, vcc
	v_cndmask_b32_e32 v100, v154, v129, vcc
	v_cndmask_b32_e32 v101, v155, v159, vcc
	v_mul_f32_e32 v132, 0xbfb8aa3b, v130
	v_mul_f32_e32 v133, 0xbfb8aa3b, v131
	v_mul_f32_e32 v156, 0xbfb8aa3b, v134
	v_mul_f32_e32 v157, 0xbfb8aa3b, v135
	v_add_f32_e32 v0, 1.0, v0
	v_cndmask_b32_e64 v102, v122, v136, s[42:43]
	v_cndmask_b32_e64 v103, v124, v137, s[42:43]
	v_cndmask_b32_e64 v104, v128, v150, s[42:43]
	v_cndmask_b32_e64 v105, v158, v151, s[42:43]
	s_waitcnt vmcnt(1)
	v_pk_fma_f32 v[100:101], v[84:85], v[100:101], v[88:89]
	v_pk_fma_f32 v[98:99], v[82:83], v[98:99], v[86:87]
	v_exp_f32_e32 v132, v132
	v_exp_f32_e32 v133, v133
	v_exp_f32_e32 v156, v156
	v_exp_f32_e32 v157, v157
	v_rcp_f32_e32 v96, v0
	v_add_f32_e32 v0, 1.0, v97
	v_pk_fma_f32 v[100:101], v[80:81], v[104:105], v[100:101]
	v_pk_fma_f32 v[98:99], v[78:79], v[102:103], v[98:99]
	v_rcp_f32_e32 v97, v0
	v_add_u32_e32 v0, 0x90, v106
	v_add_u32_e32 v120, 0xa0, v106
	v_add_u32_e32 v121, 0xb0, v106
	v_pk_mul_f32 v[106:107], v[112:113], v[114:115]
	v_pk_mul_f32 v[112:113], v[116:117], v[118:119]
	v_pk_fma_f32 v[72:73], v[72:73], v[76:77], v[100:101]
	v_pk_fma_f32 v[70:71], v[70:71], v[74:75], v[98:99]
	v_pk_mul_f32 v[72:73], v[112:113], v[72:73]
	v_pk_mul_f32 v[70:71], v[106:107], v[70:71]
	v_add_f32_e32 v132, 1.0, v132
	v_cvt_pk_bf16_f32 v70, v70, v71
	v_cvt_pk_bf16_f32 v71, v72, v73
	v_mov_b64_e32 v[72:73], s[36:37]
	v_add_f32_e32 v133, 1.0, v133
	v_add_f32_e32 v156, 1.0, v156
	v_add_f32_e32 v157, 1.0, v157
	v_mad_i64_i32 v[98:99], s[0:1], v0, s46, v[72:73]
	v_lshlrev_b64 v[100:101], 1, v[126:127]
	v_mov_b32_e32 v114, v1
	v_mov_b32_e32 v116, v1
	v_mov_b32_e32 v118, v1
	v_mov_b32_e32 v126, v1
	v_rcp_f32_e32 v132, v132
	v_rcp_f32_e32 v133, v133
	v_rcp_f32_e32 v156, v156
	v_rcp_f32_e32 v157, v157
	v_lshl_add_u64 v[98:99], v[98:99], 0, v[100:101]
	v_mov_b32_e32 v0, v1
	v_mov_b32_dpp v114, v66 row_ror:2 row_mask:0xf bank_mask:0xf
	v_mov_b32_e32 v115, v1
	v_mov_b32_dpp v116, v67 row_ror:2 row_mask:0xf bank_mask:0xf
	v_mov_b32_e32 v117, v1
	v_mov_b32_dpp v118, v68 row_ror:2 row_mask:0xf bank_mask:0xf
	v_mov_b32_e32 v119, v1
	v_mov_b32_dpp v126, v69 row_ror:2 row_mask:0xf bank_mask:0xf
	global_store_dwordx2 v[98:99], v[70:71], off
	v_mov_b32_dpp v0, v66 row_ror:1 row_mask:0xf bank_mask:0xf
	v_mov_b32_dpp v115, v67 row_ror:1 row_mask:0xf bank_mask:0xf
	v_mov_b32_dpp v117, v68 row_ror:1 row_mask:0xf bank_mask:0xf
	v_mov_b32_dpp v119, v69 row_ror:1 row_mask:0xf bank_mask:0xf
	v_cndmask_b32_e32 v70, v123, v114, vcc
	v_cndmask_b32_e32 v71, v125, v116, vcc
	v_cndmask_b32_e32 v98, v129, v118, vcc
	v_cndmask_b32_e32 v99, v159, v126, vcc
	v_cndmask_b32_e64 v102, v0, v122, s[42:43]
	v_cndmask_b32_e64 v103, v115, v124, s[42:43]
	v_cndmask_b32_e64 v104, v117, v128, s[42:43]
	v_cndmask_b32_e64 v105, v119, v158, s[42:43]
	v_pk_fma_f32 v[98:99], v[84:85], v[98:99], v[88:89]
	v_pk_fma_f32 v[70:71], v[82:83], v[70:71], v[86:87]
	v_mul_f32_e32 v94, 0xbfb8aa3b, v90
	v_mul_f32_e32 v95, 0xbfb8aa3b, v91
	v_pk_fma_f32 v[98:99], v[80:81], v[104:105], v[98:99]
	v_pk_fma_f32 v[70:71], v[78:79], v[102:103], v[70:71]
	v_exp_f32_e32 v94, v94
	v_exp_f32_e32 v95, v95
	v_pk_mul_f32 v[106:107], v[130:131], v[132:133]
	v_pk_mul_f32 v[112:113], v[134:135], v[156:157]
	v_pk_fma_f32 v[68:69], v[68:69], v[76:77], v[98:99]
	v_pk_fma_f32 v[66:67], v[66:67], v[74:75], v[70:71]
	v_pk_mul_f32 v[68:69], v[112:113], v[68:69]
	v_pk_mul_f32 v[66:67], v[106:107], v[66:67]
	v_add_f32_e32 v94, 1.0, v94
	v_cvt_pk_bf16_f32 v66, v66, v67
	v_cvt_pk_bf16_f32 v67, v68, v69
	v_mad_i64_i32 v[68:69], s[0:1], v120, s46, v[72:73]
	v_lshl_add_u64 v[68:69], v[68:69], 0, v[100:101]
	v_add_f32_e32 v95, 1.0, v95
	global_store_dwordx2 v[68:69], v[66:67], off
	v_mov_b32_e32 v66, v1
	v_mov_b32_e32 v67, v1
	v_mov_b32_e32 v68, v1
	v_mov_b32_e32 v69, v1
	v_rcp_f32_e32 v94, v94
	v_rcp_f32_e32 v95, v95
	v_mov_b32_e32 v70, v1
	v_mov_b32_dpp v66, v110 row_ror:2 row_mask:0xf bank_mask:0xf
	v_mov_b32_e32 v71, v1
	v_mov_b32_dpp v67, v111 row_ror:2 row_mask:0xf bank_mask:0xf
	v_mov_b32_e32 v98, v1
	v_mov_b32_dpp v68, v108 row_ror:2 row_mask:0xf bank_mask:0xf
	v_mov_b32_e32 v99, v1
	v_mov_b32_dpp v69, v109 row_ror:2 row_mask:0xf bank_mask:0xf
	v_mov_b32_dpp v70, v110 row_ror:1 row_mask:0xf bank_mask:0xf
	v_mov_b32_dpp v71, v111 row_ror:1 row_mask:0xf bank_mask:0xf
	v_mov_b32_dpp v98, v108 row_ror:1 row_mask:0xf bank_mask:0xf
	v_mov_b32_dpp v99, v109 row_ror:1 row_mask:0xf bank_mask:0xf
	v_cndmask_b32_e32 v66, v114, v66, vcc
	v_cndmask_b32_e32 v67, v116, v67, vcc
	v_cndmask_b32_e32 v68, v118, v68, vcc
	v_cndmask_b32_e32 v69, v126, v69, vcc
	v_cndmask_b32_e64 v70, v70, v0, s[42:43]
	v_cndmask_b32_e64 v71, v71, v115, s[42:43]
	v_cndmask_b32_e64 v98, v98, v117, s[42:43]
	v_cndmask_b32_e64 v99, v99, v119, s[42:43]
	v_pk_fma_f32 v[66:67], v[82:83], v[66:67], v[86:87]
	v_pk_fma_f32 v[68:69], v[84:85], v[68:69], v[88:89]
	v_pk_fma_f32 v[66:67], v[78:79], v[70:71], v[66:67]
	v_pk_fma_f32 v[68:69], v[80:81], v[98:99], v[68:69]
	v_pk_mul_f32 v[90:91], v[90:91], v[94:95]
	v_pk_mul_f32 v[92:93], v[92:93], v[96:97]
	v_pk_fma_f32 v[66:67], v[110:111], v[74:75], v[66:67]
	v_pk_fma_f32 v[68:69], v[108:109], v[76:77], v[68:69]
	v_pk_mul_f32 v[66:67], v[90:91], v[66:67]
	v_pk_mul_f32 v[68:69], v[92:93], v[68:69]
	v_cvt_pk_bf16_f32 v66, v66, v67
	s_nop 0
	v_cvt_pk_bf16_f32 v67, v68, v69
	v_mad_i64_i32 v[68:69], s[0:1], v121, s46, v[72:73]
	v_lshl_add_u64 v[68:69], v[68:69], 0, v[100:101]
	global_store_dwordx2 v[68:69], v[66:67], off
	s_nop 0
	v_and_b32_e32 v97, 15, v226
	v_or_b32_e32 v74, s4, v97
	v_ashrrev_i32_e32 v75, 31, v74
	v_lshl_add_u64 v[72:73], v[74:75], 3, s[38:39]
	global_load_dwordx2 v[76:77], v[72:73], off
	global_load_dwordx2 v[70:71], v[72:73], off offset:128
	global_load_dwordx2 v[68:69], v[72:73], off offset:256
	s_nop 0
	global_load_dwordx2 v[72:73], v[72:73], off offset:384
	v_ashrrev_i32_e32 v0, 1, v226
	v_and_b32_e32 v0, -8, v0
	v_add_u32_e32 v66, s21, v0
	s_waitcnt vmcnt(3)
	v_ffbh_u32_e32 v0, v77
	v_min_u32_e32 v0, 32, v0
	v_lshlrev_b64 v[76:77], v0, v[76:77]
	v_min_u32_e32 v67, 1, v76
	v_or_b32_e32 v67, v77, v67
	v_cvt_f32_u32_e32 v67, v67
	v_sub_u32_e32 v0, 32, v0
	v_ldexp_f32 v0, v67, v0
	v_mul_f32_e32 v0, 0x33800000, v0
	v_fmamk_f32 v0, v0, 0x3a800000, v210
	s_nop 0
	v_rsq_f32_e32 v0, v0
	s_nop 0
	s_nop 0
	v_ashrrev_i32_e32 v67, 31, v66
	v_pk_mul_f32 v[92:93], v[64:65], v[0:1] op_sel_hi:[1,0]
	v_pk_mul_f32 v[90:91], v[62:63], v[0:1] op_sel_hi:[1,0]
	v_pk_mul_f32 v[86:87], v[60:61], v[0:1] op_sel_hi:[1,0]
	v_pk_mul_f32 v[88:89], v[58:59], v[0:1] op_sel_hi:[1,0]
	v_lshl_add_u64 v[58:59], v[66:67], 1, s[76:77]
	v_cmp_gt_u32_e32 vcc, 2, v97
	s_and_saveexec_b64 s[0:1], vcc
	s_cbranch_execz .LBB0_123
	v_mul_u32_u24_e32 v0, 0x1600, v97
	v_lshlrev_b32_e32 v0, 1, v0
	v_cvt_pk_bf16_f32 v60, v90, v91
	v_cvt_pk_bf16_f32 v61, v92, v93
	v_lshl_add_u64 v[64:65], v[58:59], 0, v[0:1]
	v_cvt_pk_bf16_f32 v62, v88, v89
	v_cvt_pk_bf16_f32 v63, v86, v87
	global_store_dwordx2 v[64:65], v[60:61], off offset:8
	global_store_dwordx2 v[64:65], v[62:63], off offset:264

.LBB0_125:
	s_or_b64 exec, exec, s[0:1]
	v_ffbh_u32_e32 v0, v71
	v_min_u32_e32 v0, 32, v0
	v_lshlrev_b64 v[50:51], v0, v[70:71]
	v_min_u32_e32 v50, 1, v50
	v_or_b32_e32 v50, v51, v50
	v_cvt_f32_u32_e32 v50, v50
	v_sub_u32_e32 v0, 32, v0
	s_or_b32 s5, s5, 4
	v_add_u32_e32 v94, s5, v66
	v_ldexp_f32 v0, v50, v0
	v_mul_f32_e32 v0, 0x33800000, v0
	v_fmamk_f32 v0, v0, 0x3a800000, v210
	s_nop 0
	v_rsq_f32_e32 v0, v0
	s_nop 0
	s_nop 0
	v_mov_b32_e32 v84, v0
	v_ffbh_u32_e32 v0, v69
	v_min_u32_e32 v0, 32, v0
	v_pk_mul_f32 v[100:101], v[46:47], v[84:85] op_sel_hi:[1,0]
	v_lshlrev_b64 v[46:47], v0, v[68:69]
	v_min_u32_e32 v46, 1, v46
	v_or_b32_e32 v46, v47, v46
	v_cvt_f32_u32_e32 v46, v46
	v_sub_u32_e32 v0, 32, v0
	v_pk_mul_f32 v[98:99], v[48:49], v[84:85] op_sel_hi:[1,0]
	v_ldexp_f32 v0, v46, v0
	v_mul_f32_e32 v0, 0x33800000, v0
	v_fmamk_f32 v0, v0, 0x3a800000, v210
	s_nop 0
	v_rsq_f32_e32 v0, v0
	s_nop 0
	s_nop 0
	v_mov_b32_e32 v96, v0
	v_pk_mul_f32 v[102:103], v[44:45], v[96:97] op_sel_hi:[1,0]
	v_pk_mul_f32 v[112:113], v[42:43], v[96:97] op_sel_hi:[1,0]
	v_ashrrev_i32_e32 v95, 31, v94
	v_lshlrev_b64 v[54:55], 2, v[94:95]
	v_lshl_add_u64 v[42:43], s[44:45], 0, v[54:55]
	v_lshl_add_u64 v[44:45], s[60:61], 0, v[54:55]
	global_load_dwordx4 v[58:61], v[42:43], off
	global_load_dwordx4 v[62:65], v[44:45], off
	v_lshl_add_u64 v[42:43], s[2:3], 0, v[54:55]
	global_load_dwordx4 v[66:69], v[42:43], off
	v_lshl_add_u64 v[42:43], s[48:49], 0, v[54:55]
	global_load_dwordx4 v[70:73], v[42:43], off
	v_mov_b32_e32 v120, v1
	v_mov_b32_e32 v118, v1
	v_mov_b32_e32 v121, v1
	v_mov_b32_e32 v119, v1
	v_mov_b32_e32 v116, v1
	v_mov_b32_e32 v114, v1
	v_mov_b32_e32 v117, v1
	v_mov_b32_e32 v115, v1
	v_mov_b32_e32 v137, v1
	v_mov_b32_e32 v136, v1
	v_mov_b32_e32 v153, v1
	v_mov_b32_e32 v152, v1
	v_mov_b32_e32 v125, v1
	v_mov_b32_e32 v124, v1
	v_mov_b32_e32 v131, v1
	v_mov_b32_e32 v129, v1
	v_mov_b32_e32 v130, v1
	v_mov_b32_e32 v127, v1
	v_mov_b32_e32 v135, v1
	v_mov_b32_e32 v133, v1
	v_mov_b32_e32 v75, v1
	v_mov_b32_e32 v0, v1
	v_mov_b32_e32 v123, v1
	v_mov_b32_e32 v122, v1
	v_mov_b32_e32 v151, v1
	v_mov_b32_e32 v150, v1
	v_mov_b32_e32 v155, v1
	v_mov_b32_e32 v154, v1
	v_mov_b32_e32 v128, v1
	v_mov_b32_e32 v126, v1
	v_mov_b32_e32 v134, v1
	v_mov_b32_e32 v132, v1
	v_cmp_lt_u32_e32 vcc, 1, v97
	v_mov_b32_dpp v120, v90 row_ror:1 row_mask:0xf bank_mask:0xf
	v_mov_b32_dpp v118, v90 row_ror:2 row_mask:0xf bank_mask:0xf
	v_mov_b32_dpp v121, v91 row_ror:1 row_mask:0xf bank_mask:0xf
	v_mov_b32_dpp v119, v91 row_ror:2 row_mask:0xf bank_mask:0xf
	v_mov_b32_dpp v116, v92 row_ror:1 row_mask:0xf bank_mask:0xf
	v_mov_b32_dpp v114, v92 row_ror:2 row_mask:0xf bank_mask:0xf
	v_mov_b32_dpp v117, v93 row_ror:1 row_mask:0xf bank_mask:0xf
	v_mov_b32_dpp v115, v93 row_ror:2 row_mask:0xf bank_mask:0xf
	v_mov_b32_dpp v137, v100 row_ror:1 row_mask:0xf bank_mask:0xf
	v_mov_b32_dpp v136, v100 row_ror:2 row_mask:0xf bank_mask:0xf
	v_mov_b32_dpp v153, v101 row_ror:1 row_mask:0xf bank_mask:0xf
	v_mov_b32_dpp v152, v101 row_ror:2 row_mask:0xf bank_mask:0xf
	v_mov_b32_dpp v125, v98 row_ror:1 row_mask:0xf bank_mask:0xf
	v_mov_b32_dpp v124, v98 row_ror:2 row_mask:0xf bank_mask:0xf
	v_mov_b32_dpp v131, v99 row_ror:1 row_mask:0xf bank_mask:0xf
	v_mov_b32_dpp v129, v99 row_ror:2 row_mask:0xf bank_mask:0xf
	v_mov_b32_dpp v130, v112 row_ror:1 row_mask:0xf bank_mask:0xf
	v_mov_b32_dpp v127, v112 row_ror:2 row_mask:0xf bank_mask:0xf
	v_mov_b32_dpp v135, v113 row_ror:1 row_mask:0xf bank_mask:0xf
	v_mov_b32_dpp v133, v113 row_ror:2 row_mask:0xf bank_mask:0xf
	v_mov_b32_dpp v75, v102 row_ror:1 row_mask:0xf bank_mask:0xf
	v_mov_b32_dpp v0, v102 row_ror:2 row_mask:0xf bank_mask:0xf
	v_mov_b32_dpp v123, v103 row_ror:1 row_mask:0xf bank_mask:0xf
	v_mov_b32_dpp v122, v103 row_ror:2 row_mask:0xf bank_mask:0xf
	v_mov_b32_dpp v151, v82 row_ror:1 row_mask:0xf bank_mask:0xf
	v_mov_b32_dpp v150, v82 row_ror:2 row_mask:0xf bank_mask:0xf
	v_mov_b32_dpp v155, v83 row_ror:1 row_mask:0xf bank_mask:0xf
	v_mov_b32_dpp v154, v83 row_ror:2 row_mask:0xf bank_mask:0xf
	v_mov_b32_dpp v128, v80 row_ror:1 row_mask:0xf bank_mask:0xf
	v_mov_b32_dpp v126, v80 row_ror:2 row_mask:0xf bank_mask:0xf
	v_mov_b32_dpp v134, v81 row_ror:1 row_mask:0xf bank_mask:0xf
	v_mov_b32_dpp v132, v81 row_ror:2 row_mask:0xf bank_mask:0xf
	v_lshl_add_u64 v[42:43], s[96:97], 0, v[54:55]
	v_lshl_add_u64 v[44:45], s[62:63], 0, v[54:55]
	global_load_dwordx4 v[50:53], v[42:43], off
	global_load_dwordx4 v[46:49], v[44:45], off
	v_lshl_add_u64 v[42:43], s[64:65], 0, v[54:55]
	v_lshl_add_u64 v[54:55], s[66:67], 0, v[54:55]
	global_load_dwordx4 v[42:45], v[42:43], off
	v_mov_b32_e32 v104, v1
	global_load_dwordx4 v[54:57], v[54:55], off
	v_mov_b32_e32 v108, v1
	v_mov_b32_e32 v105, v1
	v_mov_b32_e32 v109, v1
	v_mov_b32_e32 v106, v1
	v_mov_b32_e32 v110, v1
	v_mov_b32_e32 v107, v1
	v_mov_b32_e32 v111, v1
	v_mov_b32_dpp v104, v88 row_ror:1 row_mask:0xf bank_mask:0xf
	v_mov_b32_dpp v108, v88 row_ror:2 row_mask:0xf bank_mask:0xf
	v_mov_b32_dpp v105, v89 row_ror:1 row_mask:0xf bank_mask:0xf
	v_mov_b32_dpp v109, v89 row_ror:2 row_mask:0xf bank_mask:0xf
	v_mov_b32_dpp v106, v86 row_ror:1 row_mask:0xf bank_mask:0xf
	v_mov_b32_dpp v110, v86 row_ror:2 row_mask:0xf bank_mask:0xf
	v_mov_b32_dpp v107, v87 row_ror:1 row_mask:0xf bank_mask:0xf
	v_mov_b32_dpp v111, v87 row_ror:2 row_mask:0xf bank_mask:0xf
	s_and_saveexec_b64 s[0:1], vcc
	s_cbranch_execz .Lcg_skip2
	s_waitcnt vmcnt(4)
	v_pk_fma_f32 v[156:157], v[60:61], v[114:115], v[72:73]
	s_nop 0
	v_pk_fma_f32 v[156:157], v[64:65], v[116:117], v[156:157]
	s_nop 0
	v_pk_fma_f32 v[92:93], v[92:93], v[68:69], v[156:157]
	v_pk_fma_f32 v[156:157], v[58:59], v[118:119], v[70:71]
	v_mul_f32_e32 v85, 0xbfb8aa3b, v93
	v_exp_f32_e32 v85, v85
	v_pk_fma_f32 v[156:157], v[62:63], v[120:121], v[156:157]
	v_mul_f32_e32 v158, 0xbfb8aa3b, v92
	v_pk_fma_f32 v[90:91], v[90:91], v[66:67], v[156:157]
	v_add_f32_e32 v85, 1.0, v85
	v_rcp_f32_e32 v159, v85
	v_mul_f32_e32 v85, 0xbfb8aa3b, v91
	v_exp_f32_e32 v85, v85
	v_mul_f32_e32 v156, 0xbfb8aa3b, v90
	v_exp_f32_e32 v158, v158
	v_exp_f32_e32 v156, v156
	v_add_f32_e32 v85, 1.0, v85
	v_rcp_f32_e32 v157, v85
	v_add_f32_e32 v158, 1.0, v158
	v_add_f32_e32 v85, 1.0, v156
	v_rcp_f32_e32 v156, v85
	v_rcp_f32_e32 v158, v158
	v_pk_mul_f32 v[90:91], v[90:91], v[156:157]
	v_pk_mul_f32 v[92:93], v[92:93], v[158:159]
	s_waitcnt vmcnt(0)
	v_pk_fma_f32 v[156:157], v[52:53], v[110:111], v[56:57]
	v_pk_fma_f32 v[158:159], v[50:51], v[108:109], v[54:55]
	v_pk_fma_f32 v[156:157], v[48:49], v[106:107], v[156:157]
	v_pk_fma_f32 v[158:159], v[46:47], v[104:105], v[158:159]
	v_pk_fma_f32 v[86:87], v[86:87], v[44:45], v[156:157]
	v_pk_fma_f32 v[88:89], v[88:89], v[42:43], v[158:159]
	v_pk_mul_f32 v[86:87], v[92:93], v[86:87]
	v_pk_mul_f32 v[88:89], v[90:91], v[88:89]
	s_nop 0
	v_cvt_pk_bf16_f32 v88, v88, v89
	v_cvt_pk_bf16_f32 v89, v86, v87
	v_mov_b64_e32 v[86:87], s[36:37]
	v_mad_i64_i32 v[86:87], s[6:7], v74, s46, v[86:87]
	v_lshl_add_u64 v[86:87], v[94:95], 1, v[86:87]
	global_store_dwordx2 v[86:87], v[88:89], off
.LBB0_127:
	s_or_b64 exec, exec, s[0:1]
	v_cmp_eq_u32_e64 s[42:43], 0, v97
	v_cndmask_b32_e32 v89, v119, v152, vcc
	v_cndmask_b32_e32 v88, v118, v136, vcc
	v_cndmask_b32_e64 v87, v153, v121, s[42:43]
	v_cndmask_b32_e64 v86, v137, v120, s[42:43]
	s_waitcnt vmcnt(4)
	v_pk_fma_f32 v[88:89], v[58:59], v[88:89], v[70:71]
	v_cndmask_b32_e32 v93, v115, v129, vcc
	v_cndmask_b32_e32 v92, v114, v124, vcc
	v_pk_fma_f32 v[86:87], v[62:63], v[86:87], v[88:89]
	v_cndmask_b32_e64 v91, v131, v117, s[42:43]
	v_cndmask_b32_e64 v90, v125, v116, s[42:43]
	v_pk_fma_f32 v[92:93], v[60:61], v[92:93], v[72:73]
	v_pk_fma_f32 v[86:87], v[100:101], v[66:67], v[86:87]
	v_pk_fma_f32 v[90:91], v[64:65], v[90:91], v[92:93]
	v_cndmask_b32_e32 v101, v152, v133, vcc
	v_cndmask_b32_e32 v100, v136, v127, vcc
	v_pk_fma_f32 v[90:91], v[98:99], v[68:69], v[90:91]
	v_cndmask_b32_e64 v99, v135, v153, s[42:43]
	v_cndmask_b32_e64 v98, v130, v137, s[42:43]
	v_pk_fma_f32 v[100:101], v[58:59], v[100:101], v[70:71]
	v_cndmask_b32_e32 v115, v129, v122, vcc
	v_pk_fma_f32 v[98:99], v[62:63], v[98:99], v[100:101]
	v_cndmask_b32_e32 v114, v124, v0, vcc
	v_pk_fma_f32 v[98:99], v[112:113], v[66:67], v[98:99]
	v_cndmask_b32_e64 v113, v123, v131, s[42:43]
	v_cndmask_b32_e64 v112, v75, v125, s[42:43]
	v_pk_fma_f32 v[114:115], v[60:61], v[114:115], v[72:73]
	v_cndmask_b32_e32 v117, v133, v154, vcc
	v_cndmask_b32_e32 v116, v127, v150, vcc
	v_pk_fma_f32 v[112:113], v[64:65], v[112:113], v[114:115]
	v_cndmask_b32_e64 v115, v155, v135, s[42:43]
	v_cndmask_b32_e64 v114, v151, v130, s[42:43]
	v_pk_fma_f32 v[58:59], v[58:59], v[116:117], v[70:71]
	v_cndmask_b32_e32 v71, v122, v132, vcc
	v_pk_fma_f32 v[58:59], v[62:63], v[114:115], v[58:59]
	v_cndmask_b32_e32 v70, v0, v126, vcc
	v_mul_f32_e32 v88, 0xbfb8aa3b, v86
	v_mul_f32_e32 v89, 0xbfb8aa3b, v87
	v_mul_f32_e32 v92, 0xbfb8aa3b, v90
	v_mul_f32_e32 v93, 0xbfb8aa3b, v91
	v_pk_fma_f32 v[58:59], v[82:83], v[66:67], v[58:59]
	v_cndmask_b32_e64 v67, v134, v123, s[42:43]
	v_cndmask_b32_e64 v66, v128, v75, s[42:43]
	v_pk_fma_f32 v[60:61], v[60:61], v[70:71], v[72:73]
	v_exp_f32_e32 v88, v88
	v_exp_f32_e32 v89, v89
	v_exp_f32_e32 v92, v92
	v_exp_f32_e32 v93, v93
	v_pk_fma_f32 v[60:61], v[64:65], v[66:67], v[60:61]
	v_mov_b32_e32 v85, v84
	v_pk_fma_f32 v[60:61], v[80:81], v[68:69], v[60:61]
	v_mov_b32_e32 v97, v96
	v_mul_f32_e32 v0, 0xbfb8aa3b, v60
	v_exp_f32_e32 v0, v0
	v_mul_f32_e32 v64, 0xbfb8aa3b, v61
	v_mov_b32_e32 v66, v84
	v_mov_b32_e32 v67, v84
	v_add_f32_e32 v88, 1.0, v88
	v_add_f32_e32 v89, 1.0, v89
	v_add_f32_e32 v92, 1.0, v92
	v_add_f32_e32 v93, 1.0, v93
	v_exp_f32_e32 v65, v64
	v_pk_mul_f32 v[40:41], v[40:41], v[66:67]
	v_pk_mul_f32 v[38:39], v[38:39], v[84:85]
	v_pk_mul_f32 v[34:35], v[34:35], v[96:97]
	v_mov_b32_e32 v85, v1
	v_mov_b32_e32 v97, v1
	v_mov_b32_e32 v115, v1
	v_mov_b32_e32 v117, v1
	v_rcp_f32_e32 v88, v88
	v_rcp_f32_e32 v89, v89
	v_rcp_f32_e32 v92, v92
	v_rcp_f32_e32 v93, v93
	v_mov_b32_e32 v66, v96
	v_mov_b32_e32 v67, v96
	v_mov_b32_e32 v84, v1
	v_mov_b32_dpp v85, v38 row_ror:2 row_mask:0xf bank_mask:0xf
	v_mov_b32_e32 v96, v1
	v_mov_b32_dpp v97, v39 row_ror:2 row_mask:0xf bank_mask:0xf
	v_mov_b32_e32 v114, v1
	v_mov_b32_dpp v115, v40 row_ror:2 row_mask:0xf bank_mask:0xf
	v_mov_b32_e32 v116, v1
	v_mov_b32_dpp v117, v41 row_ror:2 row_mask:0xf bank_mask:0xf
	v_pk_fma_f32 v[102:103], v[102:103], v[68:69], v[112:113]
	v_pk_mul_f32 v[36:37], v[36:37], v[66:67]
	v_mov_b32_dpp v84, v38 row_ror:1 row_mask:0xf bank_mask:0xf
	v_mov_b32_dpp v96, v39 row_ror:1 row_mask:0xf bank_mask:0xf
	v_mov_b32_dpp v114, v40 row_ror:1 row_mask:0xf bank_mask:0xf
	v_mov_b32_dpp v116, v41 row_ror:1 row_mask:0xf bank_mask:0xf
	v_cndmask_b32_e32 v66, v108, v85, vcc
	v_cndmask_b32_e32 v67, v109, v97, vcc
	v_cndmask_b32_e32 v68, v110, v115, vcc
	v_cndmask_b32_e32 v69, v111, v117, vcc
	v_mul_f32_e32 v100, 0xbfb8aa3b, v98
	v_mul_f32_e32 v101, 0xbfb8aa3b, v99
	v_mul_f32_e32 v112, 0xbfb8aa3b, v102
	v_mul_f32_e32 v113, 0xbfb8aa3b, v103
	v_add_f32_e32 v0, 1.0, v0
	v_cndmask_b32_e64 v70, v84, v104, s[42:43]
	v_cndmask_b32_e64 v71, v96, v105, s[42:43]
	v_cndmask_b32_e64 v72, v114, v106, s[42:43]
	v_cndmask_b32_e64 v73, v116, v107, s[42:43]
	s_waitcnt vmcnt(1)
	v_pk_fma_f32 v[68:69], v[52:53], v[68:69], v[56:57]
	v_pk_fma_f32 v[66:67], v[50:51], v[66:67], v[54:55]
	v_exp_f32_e32 v100, v100
	v_exp_f32_e32 v101, v101
	v_exp_f32_e32 v112, v112
	v_exp_f32_e32 v113, v113
	v_rcp_f32_e32 v64, v0
	v_add_f32_e32 v0, 1.0, v65
	v_pk_fma_f32 v[68:69], v[48:49], v[72:73], v[68:69]
	v_pk_fma_f32 v[66:67], v[46:47], v[70:71], v[66:67]
	v_rcp_f32_e32 v65, v0
	v_or_b32_e32 v0, 16, v74
	v_or_b32_e32 v82, 32, v74
	v_or_b32_e32 v83, 48, v74
	v_pk_mul_f32 v[74:75], v[86:87], v[88:89]
	v_pk_mul_f32 v[80:81], v[90:91], v[92:93]
	v_pk_fma_f32 v[40:41], v[40:41], v[44:45], v[68:69]
	v_pk_fma_f32 v[38:39], v[38:39], v[42:43], v[66:67]
	v_pk_mul_f32 v[40:41], v[80:81], v[40:41]
	v_pk_mul_f32 v[38:39], v[74:75], v[38:39]
	v_add_f32_e32 v100, 1.0, v100
	v_cvt_pk_bf16_f32 v38, v38, v39
	v_cvt_pk_bf16_f32 v39, v40, v41
	v_mov_b64_e32 v[40:41], s[36:37]
	v_add_f32_e32 v101, 1.0, v101
	v_add_f32_e32 v112, 1.0, v112
	v_add_f32_e32 v113, 1.0, v113
	v_mad_i64_i32 v[66:67], s[0:1], v0, s46, v[40:41]
	v_lshlrev_b64 v[68:69], 1, v[94:95]
	v_mov_b32_e32 v86, v1
	v_mov_b32_e32 v88, v1
	v_mov_b32_e32 v90, v1
	v_mov_b32_e32 v92, v1
	v_rcp_f32_e32 v100, v100
	v_rcp_f32_e32 v101, v101
	v_rcp_f32_e32 v112, v112
	v_rcp_f32_e32 v113, v113
	v_lshl_add_u64 v[66:67], v[66:67], 0, v[68:69]
	v_mov_b32_e32 v0, v1
	v_mov_b32_dpp v86, v34 row_ror:2 row_mask:0xf bank_mask:0xf
	v_mov_b32_e32 v87, v1
	v_mov_b32_dpp v88, v35 row_ror:2 row_mask:0xf bank_mask:0xf
	v_mov_b32_e32 v89, v1
	v_mov_b32_dpp v90, v36 row_ror:2 row_mask:0xf bank_mask:0xf
	v_mov_b32_e32 v91, v1
	v_mov_b32_dpp v92, v37 row_ror:2 row_mask:0xf bank_mask:0xf
	global_store_dwordx2 v[66:67], v[38:39], off
	v_mov_b32_dpp v0, v34 row_ror:1 row_mask:0xf bank_mask:0xf
	v_mov_b32_dpp v87, v35 row_ror:1 row_mask:0xf bank_mask:0xf
	v_mov_b32_dpp v89, v36 row_ror:1 row_mask:0xf bank_mask:0xf
	v_mov_b32_dpp v91, v37 row_ror:1 row_mask:0xf bank_mask:0xf
	v_cndmask_b32_e32 v38, v85, v86, vcc
	v_cndmask_b32_e32 v39, v97, v88, vcc
	v_cndmask_b32_e32 v66, v115, v90, vcc
	v_cndmask_b32_e32 v67, v117, v92, vcc
	v_cndmask_b32_e64 v70, v0, v84, s[42:43]
	v_cndmask_b32_e64 v71, v87, v96, s[42:43]
	v_cndmask_b32_e64 v72, v89, v114, s[42:43]
	v_cndmask_b32_e64 v73, v91, v116, s[42:43]
	v_pk_fma_f32 v[66:67], v[52:53], v[66:67], v[56:57]
	v_pk_fma_f32 v[38:39], v[50:51], v[38:39], v[54:55]
	v_mul_f32_e32 v62, 0xbfb8aa3b, v58
	v_mul_f32_e32 v63, 0xbfb8aa3b, v59
	v_pk_fma_f32 v[66:67], v[48:49], v[72:73], v[66:67]
	v_pk_fma_f32 v[38:39], v[46:47], v[70:71], v[38:39]
	v_exp_f32_e32 v62, v62
	v_exp_f32_e32 v63, v63
	v_pk_mul_f32 v[74:75], v[98:99], v[100:101]
	v_pk_mul_f32 v[80:81], v[102:103], v[112:113]
	v_pk_fma_f32 v[36:37], v[36:37], v[44:45], v[66:67]
	v_pk_fma_f32 v[34:35], v[34:35], v[42:43], v[38:39]
	v_pk_mul_f32 v[36:37], v[80:81], v[36:37]
	v_pk_mul_f32 v[34:35], v[74:75], v[34:35]
	v_add_f32_e32 v62, 1.0, v62
	v_cvt_pk_bf16_f32 v34, v34, v35
	v_cvt_pk_bf16_f32 v35, v36, v37
	v_mad_i64_i32 v[36:37], s[0:1], v82, s46, v[40:41]
	v_lshl_add_u64 v[36:37], v[36:37], 0, v[68:69]
	v_add_f32_e32 v63, 1.0, v63
	global_store_dwordx2 v[36:37], v[34:35], off
	v_mov_b32_e32 v34, v1
	v_mov_b32_e32 v35, v1
	v_mov_b32_e32 v36, v1
	v_mov_b32_e32 v37, v1
	v_rcp_f32_e32 v62, v62
	v_rcp_f32_e32 v63, v63
	v_mov_b32_e32 v38, v1
	v_mov_b32_dpp v34, v78 row_ror:2 row_mask:0xf bank_mask:0xf
	v_mov_b32_e32 v39, v1
	v_mov_b32_dpp v35, v79 row_ror:2 row_mask:0xf bank_mask:0xf
	v_mov_b32_e32 v66, v1
	v_mov_b32_dpp v36, v76 row_ror:2 row_mask:0xf bank_mask:0xf
	v_mov_b32_e32 v67, v1
	v_mov_b32_dpp v37, v77 row_ror:2 row_mask:0xf bank_mask:0xf
	v_mov_b32_dpp v38, v78 row_ror:1 row_mask:0xf bank_mask:0xf
	v_mov_b32_dpp v39, v79 row_ror:1 row_mask:0xf bank_mask:0xf
	v_mov_b32_dpp v66, v76 row_ror:1 row_mask:0xf bank_mask:0xf
	v_mov_b32_dpp v67, v77 row_ror:1 row_mask:0xf bank_mask:0xf
	v_cndmask_b32_e32 v34, v86, v34, vcc
	v_cndmask_b32_e32 v35, v88, v35, vcc
	v_cndmask_b32_e32 v36, v90, v36, vcc
	v_cndmask_b32_e32 v37, v92, v37, vcc
	v_cndmask_b32_e64 v38, v38, v0, s[42:43]
	v_cndmask_b32_e64 v39, v39, v87, s[42:43]
	v_cndmask_b32_e64 v66, v66, v89, s[42:43]
	v_cndmask_b32_e64 v67, v67, v91, s[42:43]
	v_pk_fma_f32 v[34:35], v[50:51], v[34:35], v[54:55]
	v_pk_fma_f32 v[36:37], v[52:53], v[36:37], v[56:57]
	v_pk_fma_f32 v[34:35], v[46:47], v[38:39], v[34:35]
	v_pk_fma_f32 v[36:37], v[48:49], v[66:67], v[36:37]
	v_pk_mul_f32 v[58:59], v[58:59], v[62:63]
	v_pk_mul_f32 v[60:61], v[60:61], v[64:65]
	v_pk_fma_f32 v[34:35], v[78:79], v[42:43], v[34:35]
	v_pk_fma_f32 v[36:37], v[76:77], v[44:45], v[36:37]
	v_pk_mul_f32 v[34:35], v[58:59], v[34:35]
	v_pk_mul_f32 v[36:37], v[60:61], v[36:37]
	v_cvt_pk_bf16_f32 v34, v34, v35
	s_nop 0
	v_cvt_pk_bf16_f32 v35, v36, v37
	v_mad_i64_i32 v[36:37], s[0:1], v83, s46, v[40:41]
	v_lshl_add_u64 v[36:37], v[36:37], 0, v[68:69]
	global_store_dwordx2 v[36:37], v[34:35], off
	s_nop 0
	v_and_b32_e32 v108, 15, v226
	v_or_b32_e32 v56, s4, v108
	v_ashrrev_i32_e32 v57, 31, v56
	v_lshl_add_u64 v[40:41], v[56:57], 3, s[38:39]
	global_load_dwordx2 v[42:43], v[40:41], off offset:1024
	global_load_dwordx2 v[38:39], v[40:41], off offset:1152
	global_load_dwordx2 v[36:37], v[40:41], off offset:1280
	s_nop 0
	global_load_dwordx2 v[40:41], v[40:41], off offset:1408
	v_ashrrev_i32_e32 v0, 1, v226
	v_and_b32_e32 v0, -8, v0
	v_add_u32_e32 v34, s21, v0
	s_waitcnt vmcnt(3)
	v_ffbh_u32_e32 v0, v43
	v_min_u32_e32 v0, 32, v0
	v_lshlrev_b64 v[42:43], v0, v[42:43]
	v_min_u32_e32 v35, 1, v42
	v_or_b32_e32 v35, v43, v35
	v_cvt_f32_u32_e32 v35, v35
	v_sub_u32_e32 v0, 32, v0
	v_ldexp_f32 v0, v35, v0
	v_mul_f32_e32 v0, 0x33800000, v0
	v_fmamk_f32 v0, v0, 0x3a800000, v210
	s_nop 0
	v_rsq_f32_e32 v0, v0
	s_nop 0
	s_nop 0
	v_ashrrev_i32_e32 v35, 31, v34
	v_pk_mul_f32 v[84:85], v[32:33], v[0:1] op_sel_hi:[1,0]
	v_pk_mul_f32 v[44:45], v[30:31], v[0:1] op_sel_hi:[1,0]
	v_pk_mul_f32 v[72:73], v[28:29], v[0:1] op_sel_hi:[1,0]
	v_pk_mul_f32 v[42:43], v[26:27], v[0:1] op_sel_hi:[1,0]
	v_lshl_add_u64 v[26:27], v[34:35], 1, s[78:79]
	v_cmp_gt_u32_e32 vcc, 2, v108
	s_and_saveexec_b64 s[0:1], vcc
	s_cbranch_execz .LBB0_129
	v_mul_u32_u24_e32 v0, 0x1600, v108
	v_lshlrev_b32_e32 v0, 1, v0
	v_cvt_pk_bf16_f32 v28, v44, v45
	v_cvt_pk_bf16_f32 v29, v84, v85
	v_lshl_add_u64 v[32:33], v[26:27], 0, v[0:1]
	v_cvt_pk_bf16_f32 v30, v42, v43
	v_cvt_pk_bf16_f32 v31, v72, v73
	global_store_dwordx2 v[32:33], v[28:29], off offset:8
	global_store_dwordx2 v[32:33], v[30:31], off offset:264

.LBB0_131:
	s_or_b64 exec, exec, s[0:1]
	v_ffbh_u32_e32 v0, v39
	v_min_u32_e32 v0, 32, v0
	v_lshlrev_b64 v[14:15], v0, v[38:39]
	v_min_u32_e32 v14, 1, v14
	v_or_b32_e32 v14, v15, v14
	v_cvt_f32_u32_e32 v14, v14
	v_sub_u32_e32 v0, 32, v0
	v_add_u32_e32 v58, s5, v34
	v_ldexp_f32 v0, v14, v0
	v_mul_f32_e32 v0, 0x33800000, v0
	v_fmamk_f32 v0, v0, 0x3a800000, v210
	s_nop 0
	v_rsq_f32_e32 v0, v0
	s_nop 0
	s_nop 0
	v_mov_b32_e32 v52, v0
	v_ffbh_u32_e32 v0, v37
	v_min_u32_e32 v0, 32, v0
	v_lshlrev_b64 v[14:15], v0, v[36:37]
	v_min_u32_e32 v14, 1, v14
	v_or_b32_e32 v14, v15, v14
	v_cvt_f32_u32_e32 v14, v14
	v_sub_u32_e32 v0, 32, v0
	v_pk_mul_f32 v[60:61], v[20:21], v[52:53] op_sel_hi:[1,0]
	v_pk_mul_f32 v[54:55], v[18:19], v[52:53] op_sel_hi:[1,0]
	v_ldexp_f32 v0, v14, v0
	v_mul_f32_e32 v0, 0x33800000, v0
	v_fmamk_f32 v0, v0, 0x3a800000, v210
	s_nop 0
	v_rsq_f32_e32 v0, v0
	s_nop 0
	s_nop 0
	v_mov_b32_e32 v62, v0
	v_pk_mul_f32 v[88:89], v[12:13], v[62:63] op_sel_hi:[1,0]
	v_pk_mul_f32 v[82:83], v[10:11], v[62:63] op_sel_hi:[1,0]
	v_ashrrev_i32_e32 v59, 31, v58
	v_lshlrev_b64 v[22:23], 2, v[58:59]
	v_lshl_add_u64 v[10:11], s[44:45], 0, v[22:23]
	v_lshl_add_u64 v[12:13], s[60:61], 0, v[22:23]
	global_load_dwordx4 v[26:29], v[10:11], off
	global_load_dwordx4 v[30:33], v[12:13], off
	v_lshl_add_u64 v[10:11], s[2:3], 0, v[22:23]
	global_load_dwordx4 v[34:37], v[10:11], off
	v_lshl_add_u64 v[10:11], s[48:49], 0, v[22:23]
	global_load_dwordx4 v[38:41], v[10:11], off
	v_mov_b32_e32 v66, v1
	v_mov_b32_e32 v87, v1
	v_mov_b32_e32 v67, v1
	v_mov_b32_e32 v86, v1
	v_mov_b32_e32 v80, v1
	v_mov_b32_e32 v91, v1
	v_mov_b32_e32 v81, v1
	v_mov_b32_e32 v90, v1
	v_mov_b32_e32 v0, v1
	v_mov_b32_e32 v97, v1
	v_mov_b32_e32 v109, v1
	v_mov_b32_e32 v96, v1
	v_mov_b32_e32 v110, v1
	v_mov_b32_e32 v99, v1
	v_mov_b32_e32 v111, v1
	v_mov_b32_e32 v98, v1
	v_mov_b32_e32 v112, v1
	v_mov_b32_e32 v93, v1
	v_mov_b32_e32 v113, v1
	v_mov_b32_e32 v92, v1
	v_mov_b32_e32 v114, v1
	v_mov_b32_e32 v95, v1
	v_mov_b32_e32 v115, v1
	v_mov_b32_e32 v94, v1
	v_mov_b32_e32 v57, v1
	v_mov_b32_e32 v101, v1
	v_mov_b32_e32 v116, v1
	v_mov_b32_e32 v100, v1
	v_mov_b32_e32 v117, v1
	v_mov_b32_e32 v103, v1
	v_mov_b32_e32 v118, v1
	v_mov_b32_e32 v102, v1
	v_cmp_lt_u32_e32 vcc, 1, v108
	v_mov_b32_dpp v66, v44 row_ror:1 row_mask:0xf bank_mask:0xf
	v_mov_b32_dpp v87, v44 row_ror:2 row_mask:0xf bank_mask:0xf
	v_mov_b32_dpp v67, v45 row_ror:1 row_mask:0xf bank_mask:0xf
	v_mov_b32_dpp v86, v45 row_ror:2 row_mask:0xf bank_mask:0xf
	v_mov_b32_dpp v80, v84 row_ror:1 row_mask:0xf bank_mask:0xf
	v_mov_b32_dpp v91, v84 row_ror:2 row_mask:0xf bank_mask:0xf
	v_mov_b32_dpp v81, v85 row_ror:1 row_mask:0xf bank_mask:0xf
	v_mov_b32_dpp v90, v85 row_ror:2 row_mask:0xf bank_mask:0xf
	v_mov_b32_dpp v0, v54 row_ror:1 row_mask:0xf bank_mask:0xf
	v_mov_b32_dpp v97, v54 row_ror:2 row_mask:0xf bank_mask:0xf
	v_mov_b32_dpp v109, v55 row_ror:1 row_mask:0xf bank_mask:0xf
	v_mov_b32_dpp v96, v55 row_ror:2 row_mask:0xf bank_mask:0xf
	v_mov_b32_dpp v110, v60 row_ror:1 row_mask:0xf bank_mask:0xf
	v_mov_b32_dpp v99, v60 row_ror:2 row_mask:0xf bank_mask:0xf
	v_mov_b32_dpp v111, v61 row_ror:1 row_mask:0xf bank_mask:0xf
	v_mov_b32_dpp v98, v61 row_ror:2 row_mask:0xf bank_mask:0xf
	v_mov_b32_dpp v112, v82 row_ror:1 row_mask:0xf bank_mask:0xf
	v_mov_b32_dpp v93, v82 row_ror:2 row_mask:0xf bank_mask:0xf
	v_mov_b32_dpp v113, v83 row_ror:1 row_mask:0xf bank_mask:0xf
	v_mov_b32_dpp v92, v83 row_ror:2 row_mask:0xf bank_mask:0xf
	v_mov_b32_dpp v114, v88 row_ror:1 row_mask:0xf bank_mask:0xf
	v_mov_b32_dpp v95, v88 row_ror:2 row_mask:0xf bank_mask:0xf
	v_mov_b32_dpp v115, v89 row_ror:1 row_mask:0xf bank_mask:0xf
	v_mov_b32_dpp v94, v89 row_ror:2 row_mask:0xf bank_mask:0xf
	v_mov_b32_dpp v57, v64 row_ror:1 row_mask:0xf bank_mask:0xf
	v_mov_b32_dpp v101, v64 row_ror:2 row_mask:0xf bank_mask:0xf
	v_mov_b32_dpp v116, v65 row_ror:1 row_mask:0xf bank_mask:0xf
	v_mov_b32_dpp v100, v65 row_ror:2 row_mask:0xf bank_mask:0xf
	v_mov_b32_dpp v117, v68 row_ror:1 row_mask:0xf bank_mask:0xf
	v_mov_b32_dpp v103, v68 row_ror:2 row_mask:0xf bank_mask:0xf
	v_mov_b32_dpp v118, v69 row_ror:1 row_mask:0xf bank_mask:0xf
	v_mov_b32_dpp v102, v69 row_ror:2 row_mask:0xf bank_mask:0xf
	v_cmp_gt_u32_e64 s[42:43], 2, v108
	v_lshl_add_u64 v[10:11], s[96:97], 0, v[22:23]
	v_lshl_add_u64 v[12:13], s[62:63], 0, v[22:23]
	global_load_dwordx4 v[18:21], v[10:11], off
	global_load_dwordx4 v[14:17], v[12:13], off
	v_lshl_add_u64 v[10:11], s[64:65], 0, v[22:23]
	v_lshl_add_u64 v[22:23], s[66:67], 0, v[22:23]
	global_load_dwordx4 v[10:13], v[10:11], off
	v_mov_b32_e32 v70, v1
	global_load_dwordx4 v[22:25], v[22:23], off
	v_mov_b32_e32 v76, v1
	v_mov_b32_e32 v71, v1
	v_mov_b32_e32 v77, v1
	v_mov_b32_e32 v74, v1
	v_mov_b32_e32 v78, v1
	v_mov_b32_e32 v75, v1
	v_mov_b32_e32 v79, v1
	v_mov_b32_dpp v70, v42 row_ror:1 row_mask:0xf bank_mask:0xf
	v_mov_b32_dpp v76, v42 row_ror:2 row_mask:0xf bank_mask:0xf
	v_mov_b32_dpp v71, v43 row_ror:1 row_mask:0xf bank_mask:0xf
	v_mov_b32_dpp v77, v43 row_ror:2 row_mask:0xf bank_mask:0xf
	v_mov_b32_dpp v74, v72 row_ror:1 row_mask:0xf bank_mask:0xf
	v_mov_b32_dpp v78, v72 row_ror:2 row_mask:0xf bank_mask:0xf
	v_mov_b32_dpp v75, v73 row_ror:1 row_mask:0xf bank_mask:0xf
	v_mov_b32_dpp v79, v73 row_ror:2 row_mask:0xf bank_mask:0xf
	s_and_saveexec_b64 s[0:1], s[42:43]
	s_xor_b64 s[0:1], exec, s[0:1]
	s_or_saveexec_b64 s[0:1], s[0:1]
	v_mov_b64_e32 v[106:107], v[98:99]
	v_mov_b64_e32 v[104:105], v[96:97]
	s_xor_b64 exec, exec, s[0:1]
	s_cbranch_execz .Lcg_skip3
	s_waitcnt vmcnt(4)
	v_pk_fma_f32 v[46:47], v[28:29], v[90:91], v[40:41] op_sel:[0,1,0] op_sel_hi:[1,0,1]
	v_mov_b64_e32 v[106:107], v[94:95]
	v_pk_fma_f32 v[46:47], v[32:33], v[80:81], v[46:47]
	v_mov_b64_e32 v[104:105], v[92:93]
	v_pk_fma_f32 v[46:47], v[84:85], v[36:37], v[46:47]
	v_pk_fma_f32 v[84:85], v[26:27], v[86:87], v[38:39] op_sel:[0,1,0] op_sel_hi:[1,0,1]
	v_mul_f32_e32 v53, 0xbfb8aa3b, v47
	v_exp_f32_e32 v53, v53
	v_pk_fma_f32 v[84:85], v[30:31], v[66:67], v[84:85]
	v_mul_f32_e32 v63, 0xbfb8aa3b, v46
	v_pk_fma_f32 v[44:45], v[44:45], v[34:35], v[84:85]
	v_add_f32_e32 v53, 1.0, v53
	v_exp_f32_e32 v63, v63
	v_rcp_f32_e32 v87, v53
	v_mul_f32_e32 v53, 0xbfb8aa3b, v45
	v_exp_f32_e32 v53, v53
	v_mul_f32_e32 v84, 0xbfb8aa3b, v44
	v_exp_f32_e32 v84, v84
	v_add_f32_e32 v63, 1.0, v63
	v_add_f32_e32 v53, 1.0, v53
	v_rcp_f32_e32 v86, v63
	v_rcp_f32_e32 v85, v53
	v_add_f32_e32 v53, 1.0, v84
	v_rcp_f32_e32 v84, v53
	v_pk_mul_f32 v[46:47], v[46:47], v[86:87]
	s_waitcnt vmcnt(0)
	v_pk_fma_f32 v[86:87], v[18:19], v[76:77], v[22:23]
	v_add_u32_e32 v53, 0x80, v56
	v_pk_fma_f32 v[86:87], v[14:15], v[70:71], v[86:87]
	v_pk_mul_f32 v[44:45], v[44:45], v[84:85]
	v_pk_fma_f32 v[42:43], v[42:43], v[10:11], v[86:87]
	v_pk_fma_f32 v[84:85], v[20:21], v[78:79], v[24:25]
	v_pk_mul_f32 v[42:43], v[44:45], v[42:43]
	v_mov_b64_e32 v[44:45], s[36:37]
	v_pk_fma_f32 v[84:85], v[16:17], v[74:75], v[84:85]
	v_mad_i64_i32 v[44:45], s[4:5], v53, s46, v[44:45]
	v_pk_fma_f32 v[72:73], v[72:73], v[12:13], v[84:85]
	v_lshl_add_u64 v[44:45], v[58:59], 1, v[44:45]
	v_mov_b64_e32 v[90:91], v[98:99]
	v_mov_b64_e32 v[86:87], v[96:97]
	v_mov_b64_e32 v[94:95], v[102:103]
	v_mov_b64_e32 v[92:93], v[100:101]
	v_pk_mul_f32 v[46:47], v[46:47], v[72:73]
	v_cvt_pk_bf16_f32 v42, v42, v43
	s_nop 0
	v_cvt_pk_bf16_f32 v43, v46, v47
	global_store_dwordx2 v[44:45], v[42:43], off

.LBB0_701:
	v_lshl_add_u32 v142, s54, 8, v174
	v_ashrrev_i32_e32 v143, 31, v142
	v_lshl_add_u64 v[140:141], v[142:143], 3, s[2:3]
	global_load_dwordx2 v[158:159], v[140:141], off
	global_load_dwordx2 v[156:157], v[140:141], off offset:128
	global_load_dwordx2 v[154:155], v[140:141], off offset:256
	global_load_dwordx2 v[152:153], v[140:141], off offset:384
	global_load_dwordx2 v[150:151], v[140:141], off offset:1024
	global_load_dwordx2 v[148:149], v[140:141], off offset:1152
	global_load_dwordx2 v[146:147], v[140:141], off offset:1280
	global_load_dwordx2 v[144:145], v[140:141], off offset:1408
	s_cmp_gt_i32 s42, 13
	s_cselect_b64 s[0:1], -1, 0
	s_cmp_lt_i32 s42, 14
	s_cselect_b64 s[6:7], -1, 0
	s_and_b64 vcc, s[6:7], exec
	s_cselect_b32 s6, 0, -14
	s_movk_i32 s7, 0xe00
	s_mov_b32 s34, 0x800000
	s_cselect_b32 s25, s18, s31
	s_cselect_b32 s28, s17, s30
	s_cselect_b32 s24, s7, 0xc00
	s_add_i32 s6, s6, s42
	v_lshl_or_b32 v140, s6, 8, v176
	v_ashrrev_i32_e32 v141, 31, v140
	s_mov_b64 s[6:7], -1
	s_waitcnt vmcnt(0)
	v_ffbh_u32_e32 v143, v159
	v_min_u32_e32 v143, 32, v143
	v_lshlrev_b64 v[158:159], v143, v[158:159]
	v_min_u32_e32 v158, 1, v158
	v_or_b32_e32 v158, v159, v158
	v_cvt_f32_u32_e32 v158, v158
	v_sub_u32_e32 v143, 32, v143
	v_ldexp_f32 v143, v158, v143
	v_mul_f32_e32 v143, 0x33800000, v143
	v_fmamk_f32 v143, v143, 0x3a800000, v210
	s_nop 0
	v_rsq_f32_e32 v143, v143
	s_nop 0
	s_nop 0
	v_mov_b32_e32 v158, v143
	v_pk_mul_f32 v[128:129], v[128:129], v[158:159] op_sel_hi:[1,0]
	v_pk_mul_f32 v[170:171], v[126:127], v[158:159] op_sel_hi:[1,0]
	v_pk_mul_f32 v[124:125], v[124:125], v[158:159] op_sel_hi:[1,0]
	v_pk_mul_f32 v[126:127], v[122:123], v[158:159] op_sel_hi:[1,0]
	s_cbranch_vccnz .LBB0_703
	v_mul_f32_e32 v122, 0xbfb8aa3b, v170
	v_exp_f32_e32 v122, v122
	v_mul_f32_e32 v143, 0xbfb8aa3b, v171
	v_exp_f32_e32 v143, v143
	v_mul_f32_e32 v123, 0xbfb8aa3b, v126
	v_exp_f32_e32 v123, v123
	v_mul_f32_e32 v159, 0xbfb8aa3b, v127
	v_add_f32_e32 v122, 1.0, v122
	v_exp_f32_e32 v159, v159
	v_rcp_f32_e32 v122, v122
	v_add_f32_e32 v143, 1.0, v143
	v_rcp_f32_e32 v143, v143
	v_add_f32_e32 v123, 1.0, v123
	v_rcp_f32_e32 v123, v123
	v_add_f32_e32 v159, 1.0, v159
	v_mul_f32_e32 v122, 0x437f0000, v122
	v_rcp_f32_e32 v159, v159
	v_max_f32_e32 v122, 1.0, v122
	v_mul_f32_e32 v143, 0x437f0000, v143
	v_rndne_f32_e32 v122, v122
	v_max_f32_e32 v143, 1.0, v143
	v_cvt_pk_u8_f32 v122, v122, 0, 0
	v_mul_f32_e32 v123, 0x437f0000, v123
	v_rndne_f32_e32 v143, v143
	v_max_f32_e32 v123, 1.0, v123
	v_cvt_pk_u8_f32 v122, v143, 1, v122
	v_mul_f32_e32 v143, 0xbfb8aa3b, v128
	v_mul_f32_e32 v159, 0x437f0000, v159
	v_rndne_f32_e32 v123, v123
	v_exp_f32_e32 v143, v143
	v_max_f32_e32 v159, 1.0, v159
	v_cvt_pk_u8_f32 v123, v123, 0, 0
	v_rndne_f32_e32 v159, v159
	v_cvt_pk_u8_f32 v123, v159, 1, v123
	v_mul_f32_e32 v159, 0xbfb8aa3b, v124
	v_exp_f32_e32 v159, v159
	v_add_f32_e32 v143, 1.0, v143
	v_rcp_f32_e32 v143, v143
	v_mul_f32_e32 v172, 0xbfb8aa3b, v129
	v_add_f32_e32 v159, 1.0, v159
	v_rcp_f32_e32 v159, v159
	v_exp_f32_e32 v172, v172
	v_mul_f32_e32 v143, 0x437f0000, v143
	v_max_f32_e32 v143, 1.0, v143
	v_rndne_f32_e32 v143, v143
	v_cvt_pk_u8_f32 v122, v143, 2, v122
	v_mul_f32_e32 v143, 0x437f0000, v159
	v_add_f32_e32 v159, 1.0, v172
	v_mul_f32_e32 v172, 0xbfb8aa3b, v125
	v_rcp_f32_e32 v159, v159
	v_exp_f32_e32 v172, v172
	v_max_f32_e32 v143, 1.0, v143
	v_rndne_f32_e32 v143, v143
	v_cvt_pk_u8_f32 v123, v143, 2, v123
	v_mul_f32_e32 v143, 0x437f0000, v159
	v_add_f32_e32 v159, 1.0, v172
	v_rcp_f32_e32 v159, v159
	v_max_f32_e32 v143, 1.0, v143
	v_rndne_f32_e32 v143, v143
	v_cvt_pk_u8_f32 v122, v143, 3, v122
	v_mul_f32_e32 v143, 0x437f0000, v159
	v_max_f32_e32 v143, 1.0, v143
	v_mov_b64_e32 v[172:173], s[30:31]
	v_rndne_f32_e32 v143, v143
	v_mad_i64_i32 v[172:173], s[6:7], v142, s55, v[172:173]
	v_cvt_pk_u8_f32 v123, v143, 3, v123
	v_lshl_add_u64 v[172:173], v[172:173], 0, v[140:141]
	s_mov_b64 s[6:7], 0
	v_mov_b32_e32 v246, v122
	v_mov_b32_e32 v247, v123
